# E49: E44 snake with the K-loop closing barrier released 8 MFMAs early instead of 4
# baseline (speedup 1.0000x reference)
.Lcm1_skip:
.LBB0_225:
	ds_read_b128 v[128:131], v157
	ds_read_b128 v[132:135], v157 offset:1024
	ds_read_b128 v[146:149], v157 offset:2048
	ds_read_b128 v[164:167], v157 offset:3072
	ds_read_b128 v[168:171], v159
	ds_read_b128 v[172:175], v159 offset:1024
	ds_read_b128 v[176:179], v159 offset:2048
	ds_read_b128 v[180:183], v159 offset:3072
	s_add_u32 s36, s22, 0xfff80080
	s_addc_u32 s37, s23, -1
	s_cmp_eq_u32 s78, 28
	s_cselect_b32 s81, s5, s37
	s_cselect_b32 s80, s14, s36
	s_cselect_b32 vcc_hi, s20, s45
	s_cselect_b32 vcc_lo, s21, s24
	s_add_i32 m0, s77, 0xc000
	ds_read_b128 v[184:187], v161
	ds_read_b128 v[188:191], v161 offset:1024
	ds_read_b128 v[192:195], v161 offset:2048
	ds_read_b128 v[196:199], v161 offset:3072
	ds_read_b128 v[200:203], v161 offset:4096
	ds_read_b128 v[204:207], v161 offset:5120
	ds_read_b128 v[208:211], v161 offset:6144
	ds_read_b128 v[212:215], v161 offset:7168
	global_load_lds_dwordx4 v140, s[22:23]
	s_add_i32 m0, s77, 0xe000
	s_nop 0
	s_add_u32 s98, s22, s6
	s_addc_u32 s99, s23, s7
	global_load_lds_dwordx4 v140, s[98:99]
	s_waitcnt vmcnt(8)
	s_waitcnt lgkmcnt(0)
	s_barrier
	s_setprio 1
	s_waitcnt lgkmcnt(0)
	v_mfma_i32_16x16x64_i8 v[0:3], v[128:131], v[184:187], v[0:3]
	v_mfma_i32_16x16x64_i8 v[0:3], v[132:135], v[188:191], v[0:3]
	v_mfma_i32_16x16x64_i8 v[56:59], v[146:149], v[184:187], v[56:59]
	v_mfma_i32_16x16x64_i8 v[56:59], v[164:167], v[188:191], v[56:59]
	v_mfma_i32_16x16x64_i8 v[88:91], v[168:171], v[184:187], v[88:91]
	v_mfma_i32_16x16x64_i8 v[88:91], v[172:175], v[188:191], v[88:91]
	v_mfma_i32_16x16x64_i8 v[120:123], v[176:179], v[184:187], v[120:123]
	v_mfma_i32_16x16x64_i8 v[120:123], v[180:183], v[188:191], v[120:123]
	v_mfma_i32_16x16x64_i8 v[116:119], v[176:179], v[192:195], v[116:119]
	v_mfma_i32_16x16x64_i8 v[116:119], v[180:183], v[196:199], v[116:119]
	v_mfma_i32_16x16x64_i8 v[84:87], v[168:171], v[192:195], v[84:87]
	v_mfma_i32_16x16x64_i8 v[84:87], v[172:175], v[196:199], v[84:87]
	v_mfma_i32_16x16x64_i8 v[52:55], v[146:149], v[192:195], v[52:55]
	v_mfma_i32_16x16x64_i8 v[52:55], v[164:167], v[196:199], v[52:55]
	v_mfma_i32_16x16x64_i8 v[4:7], v[128:131], v[192:195], v[4:7]
	v_mfma_i32_16x16x64_i8 v[4:7], v[132:135], v[196:199], v[4:7]
	s_setprio 0
	s_setprio 1
	v_mfma_i32_16x16x64_i8 v[12:15], v[128:131], v[200:203], v[12:15]
	v_mfma_i32_16x16x64_i8 v[12:15], v[132:135], v[204:207], v[12:15]
	v_mfma_i32_16x16x64_i8 v[48:51], v[146:149], v[200:203], v[48:51]
	v_mfma_i32_16x16x64_i8 v[48:51], v[164:167], v[204:207], v[48:51]
	v_mfma_i32_16x16x64_i8 v[80:83], v[168:171], v[200:203], v[80:83]
	v_mfma_i32_16x16x64_i8 v[80:83], v[172:175], v[204:207], v[80:83]
	v_mfma_i32_16x16x64_i8 v[112:115], v[176:179], v[200:203], v[112:115]
	v_mfma_i32_16x16x64_i8 v[112:115], v[180:183], v[204:207], v[112:115]
	s_setprio 2
	s_barrier
	v_mfma_i32_16x16x64_i8 v[108:111], v[176:179], v[208:211], v[108:111]
	v_mfma_i32_16x16x64_i8 v[108:111], v[180:183], v[212:215], v[108:111]
	v_mfma_i32_16x16x64_i8 v[76:79], v[168:171], v[208:211], v[76:79]
	v_mfma_i32_16x16x64_i8 v[76:79], v[172:175], v[212:215], v[76:79]
	v_mfma_i32_16x16x64_i8 v[44:47], v[146:149], v[208:211], v[44:47]
	v_mfma_i32_16x16x64_i8 v[44:47], v[164:167], v[212:215], v[44:47]
	v_mfma_i32_16x16x64_i8 v[8:11], v[128:131], v[208:211], v[8:11]
	v_mfma_i32_16x16x64_i8 v[8:11], v[132:135], v[212:215], v[8:11]
	s_setprio 0
	s_add_i32 s36, s86, s63
	s_mov_b32 m0, s36
	ds_read_b128 v[184:187], v161 offset:16384
	ds_read_b128 v[188:191], v161 offset:17408
	ds_read_b128 v[192:195], v161 offset:18432
	ds_read_b128 v[196:199], v161 offset:19456
	ds_read_b128 v[200:203], v161 offset:20480
	ds_read_b128 v[204:207], v161 offset:21504
	ds_read_b128 v[208:211], v161 offset:22528
	ds_read_b128 v[212:215], v161 offset:23552
	global_load_lds_dwordx4 v138, vcc
	s_add_i32 m0, s36, 0x2000
	s_add_i32 s36, s87, s63
	s_add_u32 s98, vcc_lo, s6
	s_addc_u32 s99, vcc_hi, s7
	global_load_lds_dwordx4 v138, s[98:99]
	s_mov_b32 m0, s36
	s_nop 0
	s_add_u32 s98, vcc_lo, s8
	s_addc_u32 s99, vcc_hi, s9
	global_load_lds_dwordx4 v138, s[98:99]
	s_add_i32 m0, s36, 0x2000
	s_nop 0
	s_add_u32 s98, vcc_lo, s10
	s_addc_u32 s99, vcc_hi, s11
	global_load_lds_dwordx4 v138, s[98:99]
	s_mov_b32 m0, s77
	s_nop 0
	global_load_lds_dwordx4 v136, s[80:81]
	s_mov_b32 m0, s97
	s_nop 0
	s_add_u32 s98, s80, s6
	s_addc_u32 s99, s81, s7
	global_load_lds_dwordx4 v136, s[98:99]
	s_waitcnt vmcnt(8)
	s_waitcnt lgkmcnt(0)
	s_barrier
	s_setprio 1
	s_waitcnt lgkmcnt(0)
	v_mfma_i32_16x16x64_i8 v[20:23], v[128:131], v[184:187], v[20:23]
	v_mfma_i32_16x16x64_i8 v[20:23], v[132:135], v[188:191], v[20:23]
	v_mfma_i32_16x16x64_i8 v[40:43], v[146:149], v[184:187], v[40:43]
	v_mfma_i32_16x16x64_i8 v[40:43], v[164:167], v[188:191], v[40:43]
	v_mfma_i32_16x16x64_i8 v[72:75], v[168:171], v[184:187], v[72:75]
	v_mfma_i32_16x16x64_i8 v[72:75], v[172:175], v[188:191], v[72:75]
	v_mfma_i32_16x16x64_i8 v[104:107], v[176:179], v[184:187], v[104:107]
	v_mfma_i32_16x16x64_i8 v[104:107], v[180:183], v[188:191], v[104:107]
	v_mfma_i32_16x16x64_i8 v[100:103], v[176:179], v[192:195], v[100:103]
	v_mfma_i32_16x16x64_i8 v[100:103], v[180:183], v[196:199], v[100:103]
	v_mfma_i32_16x16x64_i8 v[68:71], v[168:171], v[192:195], v[68:71]
	v_mfma_i32_16x16x64_i8 v[68:71], v[172:175], v[196:199], v[68:71]
	v_mfma_i32_16x16x64_i8 v[36:39], v[146:149], v[192:195], v[36:39]
	v_mfma_i32_16x16x64_i8 v[36:39], v[164:167], v[196:199], v[36:39]
	v_mfma_i32_16x16x64_i8 v[16:19], v[128:131], v[192:195], v[16:19]
	v_mfma_i32_16x16x64_i8 v[16:19], v[132:135], v[196:199], v[16:19]
	s_setprio 0
	s_setprio 1
	v_mfma_i32_16x16x64_i8 v[24:27], v[128:131], v[200:203], v[24:27]
	v_mfma_i32_16x16x64_i8 v[24:27], v[132:135], v[204:207], v[24:27]
	v_mfma_i32_16x16x64_i8 v[32:35], v[146:149], v[200:203], v[32:35]
	v_mfma_i32_16x16x64_i8 v[32:35], v[164:167], v[204:207], v[32:35]
	v_mfma_i32_16x16x64_i8 v[64:67], v[168:171], v[200:203], v[64:67]
	v_mfma_i32_16x16x64_i8 v[64:67], v[172:175], v[204:207], v[64:67]
	v_mfma_i32_16x16x64_i8 v[96:99], v[176:179], v[200:203], v[96:99]
	v_mfma_i32_16x16x64_i8 v[96:99], v[180:183], v[204:207], v[96:99]
	s_setprio 2
	s_barrier
	v_mfma_i32_16x16x64_i8 v[124:127], v[176:179], v[208:211], v[124:127]
	v_mfma_i32_16x16x64_i8 v[124:127], v[180:183], v[212:215], v[124:127]
	v_mfma_i32_16x16x64_i8 v[92:95], v[168:171], v[208:211], v[92:95]
	v_mfma_i32_16x16x64_i8 v[92:95], v[172:175], v[212:215], v[92:95]
	v_mfma_i32_16x16x64_i8 v[60:63], v[146:149], v[208:211], v[60:63]
	v_mfma_i32_16x16x64_i8 v[60:63], v[164:167], v[212:215], v[60:63]
	v_mfma_i32_16x16x64_i8 v[28:31], v[128:131], v[208:211], v[28:31]
	v_mfma_i32_16x16x64_i8 v[28:31], v[132:135], v[212:215], v[28:31]
	s_setprio 0
	s_add_i32 s36, 0, 0x18000
	v_add_u32_e32 v152, s36, v153
	s_add_i32 s37, 0, 0x1c000
	ds_read_b128 v[128:131], v152
	ds_read_b128 v[132:135], v152 offset:1024
	ds_read_b128 v[146:149], v152 offset:2048
	ds_read_b128 v[164:167], v152 offset:3072
	v_add_u32_e32 v152, s37, v153
	ds_read_b128 v[168:171], v152
	ds_read_b128 v[172:175], v152 offset:1024
	ds_read_b128 v[176:179], v152 offset:2048
	ds_read_b128 v[180:183], v152 offset:3072
	s_mov_b32 m0, s33
	ds_read_b128 v[184:187], v161 offset:32768
	ds_read_b128 v[188:191], v161 offset:33792
	ds_read_b128 v[192:195], v161 offset:34816
	ds_read_b128 v[196:199], v161 offset:35840
	ds_read_b128 v[200:203], v161 offset:36864
	ds_read_b128 v[204:207], v161 offset:37888
	ds_read_b128 v[208:211], v161 offset:38912
	ds_read_b128 v[212:215], v161 offset:39936
	s_add_u32 s98, s80, s8
	s_addc_u32 s99, s81, s9
	global_load_lds_dwordx4 v136, s[98:99]
	s_mov_b32 m0, s93
	s_nop 0
	s_add_u32 s98, s80, s10
	s_addc_u32 s99, s81, s11
	global_load_lds_dwordx4 v136, s[98:99]
	s_waitcnt vmcnt(8)
	s_waitcnt lgkmcnt(0)
	s_barrier
	s_setprio 1
	s_waitcnt lgkmcnt(0)
	v_mfma_i32_16x16x64_i8 v[0:3], v[128:131], v[184:187], v[0:3]
	v_mfma_i32_16x16x64_i8 v[0:3], v[132:135], v[188:191], v[0:3]
	v_mfma_i32_16x16x64_i8 v[56:59], v[146:149], v[184:187], v[56:59]
	v_mfma_i32_16x16x64_i8 v[56:59], v[164:167], v[188:191], v[56:59]
	v_mfma_i32_16x16x64_i8 v[88:91], v[168:171], v[184:187], v[88:91]
	v_mfma_i32_16x16x64_i8 v[88:91], v[172:175], v[188:191], v[88:91]
	v_mfma_i32_16x16x64_i8 v[120:123], v[176:179], v[184:187], v[120:123]
	v_mfma_i32_16x16x64_i8 v[120:123], v[180:183], v[188:191], v[120:123]
	v_mfma_i32_16x16x64_i8 v[116:119], v[176:179], v[192:195], v[116:119]
	v_mfma_i32_16x16x64_i8 v[116:119], v[180:183], v[196:199], v[116:119]
	v_mfma_i32_16x16x64_i8 v[84:87], v[168:171], v[192:195], v[84:87]
	v_mfma_i32_16x16x64_i8 v[84:87], v[172:175], v[196:199], v[84:87]
	v_mfma_i32_16x16x64_i8 v[52:55], v[146:149], v[192:195], v[52:55]
	v_mfma_i32_16x16x64_i8 v[52:55], v[164:167], v[196:199], v[52:55]
	v_mfma_i32_16x16x64_i8 v[4:7], v[128:131], v[192:195], v[4:7]
	v_mfma_i32_16x16x64_i8 v[4:7], v[132:135], v[196:199], v[4:7]
	s_setprio 0
	s_setprio 1
	v_mfma_i32_16x16x64_i8 v[12:15], v[128:131], v[200:203], v[12:15]
	v_mfma_i32_16x16x64_i8 v[12:15], v[132:135], v[204:207], v[12:15]
	v_mfma_i32_16x16x64_i8 v[48:51], v[146:149], v[200:203], v[48:51]
	v_mfma_i32_16x16x64_i8 v[48:51], v[164:167], v[204:207], v[48:51]
	v_mfma_i32_16x16x64_i8 v[80:83], v[168:171], v[200:203], v[80:83]
	v_mfma_i32_16x16x64_i8 v[80:83], v[172:175], v[204:207], v[80:83]
	v_mfma_i32_16x16x64_i8 v[112:115], v[176:179], v[200:203], v[112:115]
	v_mfma_i32_16x16x64_i8 v[112:115], v[180:183], v[204:207], v[112:115]
	s_setprio 2
	s_barrier
	v_mfma_i32_16x16x64_i8 v[108:111], v[176:179], v[208:211], v[108:111]
	v_mfma_i32_16x16x64_i8 v[108:111], v[180:183], v[212:215], v[108:111]
	v_mfma_i32_16x16x64_i8 v[76:79], v[168:171], v[208:211], v[76:79]
	v_mfma_i32_16x16x64_i8 v[76:79], v[172:175], v[212:215], v[76:79]
	v_mfma_i32_16x16x64_i8 v[44:47], v[146:149], v[208:211], v[44:47]
	v_mfma_i32_16x16x64_i8 v[44:47], v[164:167], v[212:215], v[44:47]
	v_mfma_i32_16x16x64_i8 v[8:11], v[128:131], v[208:211], v[8:11]
	v_mfma_i32_16x16x64_i8 v[8:11], v[132:135], v[212:215], v[8:11]
	s_setprio 0
	s_add_i32 s36, s36, s63
	s_mov_b32 m0, s36
	ds_read_b128 v[184:187], v161 offset:49152
	ds_read_b128 v[188:191], v161 offset:50176
	ds_read_b128 v[192:195], v161 offset:51200
	ds_read_b128 v[196:199], v161 offset:52224
	ds_read_b128 v[200:203], v161 offset:53248
	ds_read_b128 v[204:207], v161 offset:54272
	ds_read_b128 v[208:211], v161 offset:55296
	ds_read_b128 v[212:215], v161 offset:56320
	s_add_u32 s98, vcc_lo, s46
	s_addc_u32 s99, vcc_hi, s47
	global_load_lds_dwordx4 v138, s[98:99]
	s_add_i32 m0, s36, 0x2000
	s_add_i32 s36, s37, s63
	s_add_u32 s98, vcc_lo, s48
	s_addc_u32 s99, vcc_hi, s49
	global_load_lds_dwordx4 v138, s[98:99]
	s_mov_b32 m0, s36
	s_add_u32 s98, vcc_lo, s54
	s_addc_u32 s99, vcc_hi, s55
	global_load_lds_dwordx4 v138, s[98:99]
	s_add_i32 m0, s36, 0x2000
	s_nop 0
	s_add_u32 s98, vcc_lo, s56
	s_addc_u32 s99, vcc_hi, s57
	global_load_lds_dwordx4 v138, s[98:99]
	s_mov_b32 m0, s95
	s_nop 0
	s_add_u32 s98, s80, s46
	s_addc_u32 s99, s81, s47
	global_load_lds_dwordx4 v136, s[98:99]
	s_mov_b32 m0, s82
	s_nop 0
	s_add_u32 s98, s80, s48
	s_addc_u32 s99, s81, s49
	global_load_lds_dwordx4 v136, s[98:99]
	s_waitcnt vmcnt(8)
	s_waitcnt lgkmcnt(0)
	s_barrier
	s_setprio 1
	s_waitcnt lgkmcnt(0)
	v_mfma_i32_16x16x64_i8 v[20:23], v[128:131], v[184:187], v[20:23]
	v_mfma_i32_16x16x64_i8 v[20:23], v[132:135], v[188:191], v[20:23]
	v_mfma_i32_16x16x64_i8 v[40:43], v[146:149], v[184:187], v[40:43]
	v_mfma_i32_16x16x64_i8 v[40:43], v[164:167], v[188:191], v[40:43]
	v_mfma_i32_16x16x64_i8 v[72:75], v[168:171], v[184:187], v[72:75]
	v_mfma_i32_16x16x64_i8 v[72:75], v[172:175], v[188:191], v[72:75]
	v_mfma_i32_16x16x64_i8 v[104:107], v[176:179], v[184:187], v[104:107]
	v_mfma_i32_16x16x64_i8 v[104:107], v[180:183], v[188:191], v[104:107]
	v_mfma_i32_16x16x64_i8 v[100:103], v[176:179], v[192:195], v[100:103]
	v_mfma_i32_16x16x64_i8 v[100:103], v[180:183], v[196:199], v[100:103]
	v_mfma_i32_16x16x64_i8 v[68:71], v[168:171], v[192:195], v[68:71]
	v_mfma_i32_16x16x64_i8 v[68:71], v[172:175], v[196:199], v[68:71]
	v_mfma_i32_16x16x64_i8 v[36:39], v[146:149], v[192:195], v[36:39]
	v_mfma_i32_16x16x64_i8 v[36:39], v[164:167], v[196:199], v[36:39]
	v_mfma_i32_16x16x64_i8 v[16:19], v[128:131], v[192:195], v[16:19]
	v_mfma_i32_16x16x64_i8 v[16:19], v[132:135], v[196:199], v[16:19]
	s_setprio 0
	s_setprio 1
	v_mfma_i32_16x16x64_i8 v[24:27], v[128:131], v[200:203], v[24:27]
	v_mfma_i32_16x16x64_i8 v[24:27], v[132:135], v[204:207], v[24:27]
	v_mfma_i32_16x16x64_i8 v[32:35], v[146:149], v[200:203], v[32:35]
	v_mfma_i32_16x16x64_i8 v[32:35], v[164:167], v[204:207], v[32:35]
	v_mfma_i32_16x16x64_i8 v[64:67], v[168:171], v[200:203], v[64:67]
	v_mfma_i32_16x16x64_i8 v[64:67], v[172:175], v[204:207], v[64:67]
	v_mfma_i32_16x16x64_i8 v[96:99], v[176:179], v[200:203], v[96:99]
	v_mfma_i32_16x16x64_i8 v[96:99], v[180:183], v[204:207], v[96:99]
	s_setprio 2
	s_barrier
	v_mfma_i32_16x16x64_i8 v[124:127], v[176:179], v[208:211], v[124:127]
	v_mfma_i32_16x16x64_i8 v[124:127], v[180:183], v[212:215], v[124:127]
	v_mfma_i32_16x16x64_i8 v[92:95], v[168:171], v[208:211], v[92:95]
	v_mfma_i32_16x16x64_i8 v[92:95], v[172:175], v[212:215], v[92:95]
	v_mfma_i32_16x16x64_i8 v[60:63], v[146:149], v[208:211], v[60:63]
	v_mfma_i32_16x16x64_i8 v[60:63], v[164:167], v[212:215], v[60:63]
	v_mfma_i32_16x16x64_i8 v[28:31], v[128:131], v[208:211], v[28:31]
	v_mfma_i32_16x16x64_i8 v[28:31], v[132:135], v[212:215], v[28:31]
	s_setprio 0
	s_add_i32 s78, s78, 2
	s_add_u32 s24, s24, 0x100
	s_addc_u32 s45, s45, 0
	s_add_u32 s22, s22, 0x100
	s_addc_u32 s23, s23, 0
	s_cmp_gt_u32 s78, 29
	s_cbranch_scc0 .LBB0_225
	v_readlane_b32 s14, v250, 9
	v_readlane_b32 s15, v250, 10
	s_and_b64 vcc, exec, s[14:15]
	s_cbranch_vccz .LBB0_228
	s_barrier

.LBB0_298:
	ds_read_b128 v[128:131], v153
	ds_read_b128 v[132:135], v153 offset:1024
	ds_read_b128 v[146:149], v153 offset:2048
	ds_read_b128 v[158:161], v153 offset:3072
	ds_read_b128 v[162:165], v154
	ds_read_b128 v[166:169], v154 offset:1024
	ds_read_b128 v[170:173], v154 offset:2048
	ds_read_b128 v[174:177], v154 offset:3072
	s_add_u32 s36, s78, 0xfff00080
	s_addc_u32 s37, s79, -1
	s_cmp_eq_u32 s81, 60
	s_cselect_b32 s97, s5, s37
	s_cselect_b32 s96, s14, s36
	s_cselect_b32 vcc_hi, s20, s80
	s_cselect_b32 vcc_lo, s21, s22
	s_add_i32 m0, s33, 0xc000
	ds_read_b128 v[178:181], v155
	ds_read_b128 v[182:185], v155 offset:1024
	ds_read_b128 v[186:189], v155 offset:2048
	ds_read_b128 v[190:193], v155 offset:3072
	ds_read_b128 v[194:197], v155 offset:4096
	ds_read_b128 v[198:201], v155 offset:5120
	ds_read_b128 v[202:205], v155 offset:6144
	ds_read_b128 v[206:209], v155 offset:7168
	global_load_lds_dwordx4 v140, s[78:79]
	s_add_i32 m0, s33, 0xe000
	s_nop 0
	s_add_u32 s98, s78, s0
	s_addc_u32 s99, s79, s1
	global_load_lds_dwordx4 v140, s[98:99]
	s_waitcnt vmcnt(8)
	s_waitcnt lgkmcnt(0)
	s_barrier
	s_setprio 1
	s_waitcnt lgkmcnt(0)
	v_mfma_f32_16x16x32_bf16 v[124:127], v[128:131], v[178:181], v[124:127]
	v_mfma_f32_16x16x32_bf16 v[124:127], v[132:135], v[182:185], v[124:127]
	v_mfma_f32_16x16x32_bf16 v[120:123], v[146:149], v[178:181], v[120:123]
	v_mfma_f32_16x16x32_bf16 v[120:123], v[158:161], v[182:185], v[120:123]
	v_mfma_f32_16x16x32_bf16 v[116:119], v[162:165], v[178:181], v[116:119]
	v_mfma_f32_16x16x32_bf16 v[116:119], v[166:169], v[182:185], v[116:119]
	v_mfma_f32_16x16x32_bf16 v[104:107], v[170:173], v[178:181], v[104:107]
	v_mfma_f32_16x16x32_bf16 v[104:107], v[174:177], v[182:185], v[104:107]
	v_mfma_f32_16x16x32_bf16 v[88:91], v[170:173], v[186:189], v[88:91]
	v_mfma_f32_16x16x32_bf16 v[88:91], v[174:177], v[190:193], v[88:91]
	v_mfma_f32_16x16x32_bf16 v[96:99], v[162:165], v[186:189], v[96:99]
	v_mfma_f32_16x16x32_bf16 v[96:99], v[166:169], v[190:193], v[96:99]
	v_mfma_f32_16x16x32_bf16 v[108:111], v[146:149], v[186:189], v[108:111]
	v_mfma_f32_16x16x32_bf16 v[108:111], v[158:161], v[190:193], v[108:111]
	v_mfma_f32_16x16x32_bf16 v[112:115], v[128:131], v[186:189], v[112:115]
	v_mfma_f32_16x16x32_bf16 v[112:115], v[132:135], v[190:193], v[112:115]
	s_setprio 0
	s_setprio 1
	v_mfma_f32_16x16x32_bf16 v[100:103], v[128:131], v[194:197], v[100:103]
	v_mfma_f32_16x16x32_bf16 v[100:103], v[132:135], v[198:201], v[100:103]
	v_mfma_f32_16x16x32_bf16 v[92:95], v[146:149], v[194:197], v[92:95]
	v_mfma_f32_16x16x32_bf16 v[92:95], v[158:161], v[198:201], v[92:95]
	v_mfma_f32_16x16x32_bf16 v[80:83], v[162:165], v[194:197], v[80:83]
	v_mfma_f32_16x16x32_bf16 v[80:83], v[166:169], v[198:201], v[80:83]
	v_mfma_f32_16x16x32_bf16 v[72:75], v[170:173], v[194:197], v[72:75]
	v_mfma_f32_16x16x32_bf16 v[72:75], v[174:177], v[198:201], v[72:75]
	s_setprio 2
	s_barrier
	v_mfma_f32_16x16x32_bf16 v[64:67], v[170:173], v[202:205], v[64:67]
	v_mfma_f32_16x16x32_bf16 v[64:67], v[174:177], v[206:209], v[64:67]
	v_mfma_f32_16x16x32_bf16 v[68:71], v[162:165], v[202:205], v[68:71]
	v_mfma_f32_16x16x32_bf16 v[68:71], v[166:169], v[206:209], v[68:71]
	v_mfma_f32_16x16x32_bf16 v[76:79], v[146:149], v[202:205], v[76:79]
	v_mfma_f32_16x16x32_bf16 v[76:79], v[158:161], v[206:209], v[76:79]
	v_mfma_f32_16x16x32_bf16 v[84:87], v[128:131], v[202:205], v[84:87]
	v_mfma_f32_16x16x32_bf16 v[84:87], v[132:135], v[206:209], v[84:87]
	s_setprio 0
	s_add_i32 s36, s82, s63
	s_mov_b32 m0, s36
	ds_read_b128 v[178:181], v155 offset:16384
	ds_read_b128 v[182:185], v155 offset:17408
	ds_read_b128 v[186:189], v155 offset:18432
	ds_read_b128 v[190:193], v155 offset:19456
	ds_read_b128 v[194:197], v155 offset:20480
	ds_read_b128 v[198:201], v155 offset:21504
	ds_read_b128 v[202:205], v155 offset:22528
	ds_read_b128 v[206:209], v155 offset:23552
	global_load_lds_dwordx4 v138, vcc
	s_add_i32 m0, s36, 0x2000
	s_add_i32 s36, s83, s63
	s_add_u32 s98, vcc_lo, s0
	s_addc_u32 s99, vcc_hi, s1
	global_load_lds_dwordx4 v138, s[98:99]
	s_mov_b32 m0, s36
	s_nop 0
	s_add_u32 s98, vcc_lo, s6
	s_addc_u32 s99, vcc_hi, s7
	global_load_lds_dwordx4 v138, s[98:99]
	s_add_i32 m0, s36, 0x2000
	s_nop 0
	s_add_u32 s98, vcc_lo, s8
	s_addc_u32 s99, vcc_hi, s9
	global_load_lds_dwordx4 v138, s[98:99]
	s_mov_b32 m0, s33
	s_nop 0
	global_load_lds_dwordx4 v136, s[96:97]
	s_mov_b32 m0, s55
	s_nop 0
	s_add_u32 s98, s96, s0
	s_addc_u32 s99, s97, s1
	global_load_lds_dwordx4 v136, s[98:99]
	s_waitcnt vmcnt(8)
	s_waitcnt lgkmcnt(0)
	s_barrier
	s_setprio 1
	s_waitcnt lgkmcnt(0)
	v_mfma_f32_16x16x32_bf16 v[60:63], v[128:131], v[178:181], v[60:63]
	v_mfma_f32_16x16x32_bf16 v[60:63], v[132:135], v[182:185], v[60:63]
	v_mfma_f32_16x16x32_bf16 v[56:59], v[146:149], v[178:181], v[56:59]
	v_mfma_f32_16x16x32_bf16 v[56:59], v[158:161], v[182:185], v[56:59]
	v_mfma_f32_16x16x32_bf16 v[48:51], v[162:165], v[178:181], v[48:51]
	v_mfma_f32_16x16x32_bf16 v[48:51], v[166:169], v[182:185], v[48:51]
	v_mfma_f32_16x16x32_bf16 v[40:43], v[170:173], v[178:181], v[40:43]
	v_mfma_f32_16x16x32_bf16 v[40:43], v[174:177], v[182:185], v[40:43]
	v_mfma_f32_16x16x32_bf16 v[24:27], v[170:173], v[186:189], v[24:27]
	v_mfma_f32_16x16x32_bf16 v[24:27], v[174:177], v[190:193], v[24:27]
	v_mfma_f32_16x16x32_bf16 v[32:35], v[162:165], v[186:189], v[32:35]
	v_mfma_f32_16x16x32_bf16 v[32:35], v[166:169], v[190:193], v[32:35]
	v_mfma_f32_16x16x32_bf16 v[44:47], v[146:149], v[186:189], v[44:47]
	v_mfma_f32_16x16x32_bf16 v[44:47], v[158:161], v[190:193], v[44:47]
	v_mfma_f32_16x16x32_bf16 v[52:55], v[128:131], v[186:189], v[52:55]
	v_mfma_f32_16x16x32_bf16 v[52:55], v[132:135], v[190:193], v[52:55]
	s_setprio 0
	s_setprio 1
	v_mfma_f32_16x16x32_bf16 v[36:39], v[128:131], v[194:197], v[36:39]
	v_mfma_f32_16x16x32_bf16 v[36:39], v[132:135], v[198:201], v[36:39]
	v_mfma_f32_16x16x32_bf16 v[28:31], v[146:149], v[194:197], v[28:31]
	v_mfma_f32_16x16x32_bf16 v[28:31], v[158:161], v[198:201], v[28:31]
	v_mfma_f32_16x16x32_bf16 v[16:19], v[162:165], v[194:197], v[16:19]
	v_mfma_f32_16x16x32_bf16 v[16:19], v[166:169], v[198:201], v[16:19]
	v_mfma_f32_16x16x32_bf16 v[8:11], v[170:173], v[194:197], v[8:11]
	v_mfma_f32_16x16x32_bf16 v[8:11], v[174:177], v[198:201], v[8:11]
	s_setprio 2
	s_barrier
	v_mfma_f32_16x16x32_bf16 v[0:3], v[170:173], v[202:205], v[0:3]
	v_mfma_f32_16x16x32_bf16 v[0:3], v[174:177], v[206:209], v[0:3]
	v_mfma_f32_16x16x32_bf16 v[4:7], v[162:165], v[202:205], v[4:7]
	v_mfma_f32_16x16x32_bf16 v[4:7], v[166:169], v[206:209], v[4:7]
	v_mfma_f32_16x16x32_bf16 v[12:15], v[146:149], v[202:205], v[12:15]
	v_mfma_f32_16x16x32_bf16 v[12:15], v[158:161], v[206:209], v[12:15]
	v_mfma_f32_16x16x32_bf16 v[20:23], v[128:131], v[202:205], v[20:23]
	v_mfma_f32_16x16x32_bf16 v[20:23], v[132:135], v[206:209], v[20:23]
	s_setprio 0
	s_add_i32 s36, 0, 0x18000
	v_add_u32_e32 v157, s36, v152
	s_add_i32 s37, 0, 0x1c000
	ds_read_b128 v[128:131], v157
	ds_read_b128 v[132:135], v157 offset:1024
	ds_read_b128 v[146:149], v157 offset:2048
	ds_read_b128 v[158:161], v157 offset:3072
	v_add_u32_e32 v157, s37, v152
	ds_read_b128 v[162:165], v157
	ds_read_b128 v[166:169], v157 offset:1024
	ds_read_b128 v[170:173], v157 offset:2048
	ds_read_b128 v[174:177], v157 offset:3072
	s_mov_b32 m0, s57
	ds_read_b128 v[178:181], v155 offset:32768
	ds_read_b128 v[182:185], v155 offset:33792
	ds_read_b128 v[186:189], v155 offset:34816
	ds_read_b128 v[190:193], v155 offset:35840
	ds_read_b128 v[194:197], v155 offset:36864
	ds_read_b128 v[198:201], v155 offset:37888
	ds_read_b128 v[202:205], v155 offset:38912
	ds_read_b128 v[206:209], v155 offset:39936
	s_add_u32 s98, s96, s6
	s_addc_u32 s99, s97, s7
	global_load_lds_dwordx4 v136, s[98:99]
	s_mov_b32 m0, s59
	s_nop 0
	s_add_u32 s98, s96, s8
	s_addc_u32 s99, s97, s9
	global_load_lds_dwordx4 v136, s[98:99]
	s_waitcnt vmcnt(8)
	s_waitcnt lgkmcnt(0)
	s_barrier
	s_setprio 1
	s_waitcnt lgkmcnt(0)
	v_mfma_f32_16x16x32_bf16 v[124:127], v[128:131], v[178:181], v[124:127]
	v_mfma_f32_16x16x32_bf16 v[124:127], v[132:135], v[182:185], v[124:127]
	v_mfma_f32_16x16x32_bf16 v[120:123], v[146:149], v[178:181], v[120:123]
	v_mfma_f32_16x16x32_bf16 v[120:123], v[158:161], v[182:185], v[120:123]
	v_mfma_f32_16x16x32_bf16 v[116:119], v[162:165], v[178:181], v[116:119]
	v_mfma_f32_16x16x32_bf16 v[116:119], v[166:169], v[182:185], v[116:119]
	v_mfma_f32_16x16x32_bf16 v[104:107], v[170:173], v[178:181], v[104:107]
	v_mfma_f32_16x16x32_bf16 v[104:107], v[174:177], v[182:185], v[104:107]
	v_mfma_f32_16x16x32_bf16 v[88:91], v[170:173], v[186:189], v[88:91]
	v_mfma_f32_16x16x32_bf16 v[88:91], v[174:177], v[190:193], v[88:91]
	v_mfma_f32_16x16x32_bf16 v[96:99], v[162:165], v[186:189], v[96:99]
	v_mfma_f32_16x16x32_bf16 v[96:99], v[166:169], v[190:193], v[96:99]
	v_mfma_f32_16x16x32_bf16 v[108:111], v[146:149], v[186:189], v[108:111]
	v_mfma_f32_16x16x32_bf16 v[108:111], v[158:161], v[190:193], v[108:111]
	v_mfma_f32_16x16x32_bf16 v[112:115], v[128:131], v[186:189], v[112:115]
	v_mfma_f32_16x16x32_bf16 v[112:115], v[132:135], v[190:193], v[112:115]
	s_setprio 0
	s_setprio 1
	v_mfma_f32_16x16x32_bf16 v[100:103], v[128:131], v[194:197], v[100:103]
	v_mfma_f32_16x16x32_bf16 v[100:103], v[132:135], v[198:201], v[100:103]
	v_mfma_f32_16x16x32_bf16 v[92:95], v[146:149], v[194:197], v[92:95]
	v_mfma_f32_16x16x32_bf16 v[92:95], v[158:161], v[198:201], v[92:95]
	v_mfma_f32_16x16x32_bf16 v[80:83], v[162:165], v[194:197], v[80:83]
	v_mfma_f32_16x16x32_bf16 v[80:83], v[166:169], v[198:201], v[80:83]
	v_mfma_f32_16x16x32_bf16 v[72:75], v[170:173], v[194:197], v[72:75]
	v_mfma_f32_16x16x32_bf16 v[72:75], v[174:177], v[198:201], v[72:75]
	s_setprio 2
	s_barrier
	v_mfma_f32_16x16x32_bf16 v[64:67], v[170:173], v[202:205], v[64:67]
	v_mfma_f32_16x16x32_bf16 v[64:67], v[174:177], v[206:209], v[64:67]
	v_mfma_f32_16x16x32_bf16 v[68:71], v[162:165], v[202:205], v[68:71]
	v_mfma_f32_16x16x32_bf16 v[68:71], v[166:169], v[206:209], v[68:71]
	v_mfma_f32_16x16x32_bf16 v[76:79], v[146:149], v[202:205], v[76:79]
	v_mfma_f32_16x16x32_bf16 v[76:79], v[158:161], v[206:209], v[76:79]
	v_mfma_f32_16x16x32_bf16 v[84:87], v[128:131], v[202:205], v[84:87]
	v_mfma_f32_16x16x32_bf16 v[84:87], v[132:135], v[206:209], v[84:87]
	s_setprio 0
	s_add_i32 s36, s36, s63
	s_mov_b32 m0, s36
	ds_read_b128 v[178:181], v155 offset:49152
	ds_read_b128 v[182:185], v155 offset:50176
	ds_read_b128 v[186:189], v155 offset:51200
	ds_read_b128 v[190:193], v155 offset:52224
	ds_read_b128 v[194:197], v155 offset:53248
	ds_read_b128 v[198:201], v155 offset:54272
	ds_read_b128 v[202:205], v155 offset:55296
	ds_read_b128 v[206:209], v155 offset:56320
	s_add_u32 s98, vcc_lo, s24
	s_addc_u32 s99, vcc_hi, s25
	global_load_lds_dwordx4 v138, s[98:99]
	s_add_i32 m0, s36, 0x2000
	s_add_i32 s36, s37, s63
	s_add_u32 s98, vcc_lo, s34
	s_addc_u32 s99, vcc_hi, s35
	global_load_lds_dwordx4 v138, s[98:99]
	s_mov_b32 m0, s36
	s_add_u32 s98, vcc_lo, s12
	s_addc_u32 s99, vcc_hi, s13
	global_load_lds_dwordx4 v138, s[98:99]
	s_add_i32 m0, s36, 0x2000
	s_nop 0
	s_add_u32 s98, vcc_lo, s18
	s_addc_u32 s99, vcc_hi, s19
	global_load_lds_dwordx4 v138, s[98:99]
	s_mov_b32 m0, s68
	s_nop 0
	s_add_u32 s98, s96, s24
	s_addc_u32 s99, s97, s25
	global_load_lds_dwordx4 v136, s[98:99]
	s_mov_b32 m0, s69
	s_nop 0
	s_add_u32 s98, s96, s34
	s_addc_u32 s99, s97, s35
	global_load_lds_dwordx4 v136, s[98:99]
	s_waitcnt vmcnt(8)
	s_waitcnt lgkmcnt(0)
	s_barrier
	s_setprio 1
	s_waitcnt lgkmcnt(0)
	v_mfma_f32_16x16x32_bf16 v[60:63], v[128:131], v[178:181], v[60:63]
	v_mfma_f32_16x16x32_bf16 v[60:63], v[132:135], v[182:185], v[60:63]
	v_mfma_f32_16x16x32_bf16 v[56:59], v[146:149], v[178:181], v[56:59]
	v_mfma_f32_16x16x32_bf16 v[56:59], v[158:161], v[182:185], v[56:59]
	v_mfma_f32_16x16x32_bf16 v[48:51], v[162:165], v[178:181], v[48:51]
	v_mfma_f32_16x16x32_bf16 v[48:51], v[166:169], v[182:185], v[48:51]
	v_mfma_f32_16x16x32_bf16 v[40:43], v[170:173], v[178:181], v[40:43]
	v_mfma_f32_16x16x32_bf16 v[40:43], v[174:177], v[182:185], v[40:43]
	v_mfma_f32_16x16x32_bf16 v[24:27], v[170:173], v[186:189], v[24:27]
	v_mfma_f32_16x16x32_bf16 v[24:27], v[174:177], v[190:193], v[24:27]
	v_mfma_f32_16x16x32_bf16 v[32:35], v[162:165], v[186:189], v[32:35]
	v_mfma_f32_16x16x32_bf16 v[32:35], v[166:169], v[190:193], v[32:35]
	v_mfma_f32_16x16x32_bf16 v[44:47], v[146:149], v[186:189], v[44:47]
	v_mfma_f32_16x16x32_bf16 v[44:47], v[158:161], v[190:193], v[44:47]
	v_mfma_f32_16x16x32_bf16 v[52:55], v[128:131], v[186:189], v[52:55]
	v_mfma_f32_16x16x32_bf16 v[52:55], v[132:135], v[190:193], v[52:55]
	s_setprio 0
	s_setprio 1
	v_mfma_f32_16x16x32_bf16 v[36:39], v[128:131], v[194:197], v[36:39]
	v_mfma_f32_16x16x32_bf16 v[36:39], v[132:135], v[198:201], v[36:39]
	v_mfma_f32_16x16x32_bf16 v[28:31], v[146:149], v[194:197], v[28:31]
	v_mfma_f32_16x16x32_bf16 v[28:31], v[158:161], v[198:201], v[28:31]
	v_mfma_f32_16x16x32_bf16 v[16:19], v[162:165], v[194:197], v[16:19]
	v_mfma_f32_16x16x32_bf16 v[16:19], v[166:169], v[198:201], v[16:19]
	v_mfma_f32_16x16x32_bf16 v[8:11], v[170:173], v[194:197], v[8:11]
	v_mfma_f32_16x16x32_bf16 v[8:11], v[174:177], v[198:201], v[8:11]
	s_setprio 2
	s_barrier
	v_mfma_f32_16x16x32_bf16 v[0:3], v[170:173], v[202:205], v[0:3]
	v_mfma_f32_16x16x32_bf16 v[0:3], v[174:177], v[206:209], v[0:3]
	v_mfma_f32_16x16x32_bf16 v[4:7], v[162:165], v[202:205], v[4:7]
	v_mfma_f32_16x16x32_bf16 v[4:7], v[166:169], v[206:209], v[4:7]
	v_mfma_f32_16x16x32_bf16 v[12:15], v[146:149], v[202:205], v[12:15]
	v_mfma_f32_16x16x32_bf16 v[12:15], v[158:161], v[206:209], v[12:15]
	v_mfma_f32_16x16x32_bf16 v[20:23], v[128:131], v[202:205], v[20:23]
	v_mfma_f32_16x16x32_bf16 v[20:23], v[132:135], v[206:209], v[20:23]
	s_setprio 0
	s_add_i32 s81, s81, 2
	s_add_u32 s22, s22, 0x100
	s_addc_u32 s80, s80, 0
	s_add_u32 s78, s78, 0x100
	s_addc_u32 s79, s79, 0
	s_cmp_gt_u32 s81, 61
	s_cbranch_scc0 .LBB0_298
	s_and_b64 vcc, exec, s[26:27]
	s_cbranch_vccz .LBB0_301
	s_barrier

.LBB0_627:
	ds_read_b128 v[128:131], v151
	ds_read_b128 v[142:145], v151 offset:1024
	ds_read_b128 v[146:149], v151 offset:2048
	ds_read_b128 v[154:157], v151 offset:3072
	ds_read_b128 v[158:161], v152
	ds_read_b128 v[162:165], v152 offset:1024
	ds_read_b128 v[166:169], v152 offset:2048
	ds_read_b128 v[170:173], v152 offset:3072
	s_add_u32 s50, s60, 0xfff00080
	s_addc_u32 s51, s61, -1
	s_cmp_eq_u32 s62, 60
	s_cselect_b32 s77, s5, s51
	s_cselect_b32 s76, s49, s50
	s_cselect_b32 s79, s47, s75
	s_cselect_b32 s78, s59, s74
	s_add_i32 m0, s20, 0xc000
	ds_read_b128 v[174:177], v153
	ds_read_b128 v[178:181], v153 offset:1024
	ds_read_b128 v[182:185], v153 offset:2048
	ds_read_b128 v[186:189], v153 offset:3072
	ds_read_b128 v[190:193], v153 offset:4096
	ds_read_b128 v[194:197], v153 offset:5120
	ds_read_b128 v[198:201], v153 offset:6144
	ds_read_b128 v[202:205], v153 offset:7168
	global_load_lds_dwordx4 v136, s[60:61]
	s_add_i32 m0, s20, 0xe000
	s_nop 0
	s_add_u32 s98, s60, s6
	s_addc_u32 s99, s61, s7
	global_load_lds_dwordx4 v136, s[98:99]
	s_waitcnt vmcnt(8)
	s_waitcnt lgkmcnt(0)
	s_barrier
	s_setprio 1
	s_waitcnt lgkmcnt(0)
	v_mfma_f32_16x16x32_bf16 v[124:127], v[128:131], v[174:177], v[124:127]
	v_mfma_f32_16x16x32_bf16 v[124:127], v[142:145], v[178:181], v[124:127]
	v_mfma_f32_16x16x32_bf16 v[120:123], v[146:149], v[174:177], v[120:123]
	v_mfma_f32_16x16x32_bf16 v[120:123], v[154:157], v[178:181], v[120:123]
	v_mfma_f32_16x16x32_bf16 v[92:95], v[158:161], v[174:177], v[92:95]
	v_mfma_f32_16x16x32_bf16 v[92:95], v[162:165], v[178:181], v[92:95]
	v_mfma_f32_16x16x32_bf16 v[88:91], v[166:169], v[174:177], v[88:91]
	v_mfma_f32_16x16x32_bf16 v[88:91], v[170:173], v[178:181], v[88:91]
	v_mfma_f32_16x16x32_bf16 v[80:83], v[166:169], v[182:185], v[80:83]
	v_mfma_f32_16x16x32_bf16 v[80:83], v[170:173], v[186:189], v[80:83]
	v_mfma_f32_16x16x32_bf16 v[84:87], v[158:161], v[182:185], v[84:87]
	v_mfma_f32_16x16x32_bf16 v[84:87], v[162:165], v[186:189], v[84:87]
	v_mfma_f32_16x16x32_bf16 v[112:115], v[146:149], v[182:185], v[112:115]
	v_mfma_f32_16x16x32_bf16 v[112:115], v[154:157], v[186:189], v[112:115]
	v_mfma_f32_16x16x32_bf16 v[116:119], v[128:131], v[182:185], v[116:119]
	v_mfma_f32_16x16x32_bf16 v[116:119], v[142:145], v[186:189], v[116:119]
	s_setprio 0
	s_setprio 1
	v_mfma_f32_16x16x32_bf16 v[108:111], v[128:131], v[190:193], v[108:111]
	v_mfma_f32_16x16x32_bf16 v[108:111], v[142:145], v[194:197], v[108:111]
	v_mfma_f32_16x16x32_bf16 v[104:107], v[146:149], v[190:193], v[104:107]
	v_mfma_f32_16x16x32_bf16 v[104:107], v[154:157], v[194:197], v[104:107]
	v_mfma_f32_16x16x32_bf16 v[76:79], v[158:161], v[190:193], v[76:79]
	v_mfma_f32_16x16x32_bf16 v[76:79], v[162:165], v[194:197], v[76:79]
	v_mfma_f32_16x16x32_bf16 v[72:75], v[166:169], v[190:193], v[72:75]
	v_mfma_f32_16x16x32_bf16 v[72:75], v[170:173], v[194:197], v[72:75]
	s_setprio 2
	s_barrier
	v_mfma_f32_16x16x32_bf16 v[64:67], v[166:169], v[198:201], v[64:67]
	v_mfma_f32_16x16x32_bf16 v[64:67], v[170:173], v[202:205], v[64:67]
	v_mfma_f32_16x16x32_bf16 v[68:71], v[158:161], v[198:201], v[68:71]
	v_mfma_f32_16x16x32_bf16 v[68:71], v[162:165], v[202:205], v[68:71]
	v_mfma_f32_16x16x32_bf16 v[96:99], v[146:149], v[198:201], v[96:99]
	v_mfma_f32_16x16x32_bf16 v[96:99], v[154:157], v[202:205], v[96:99]
	v_mfma_f32_16x16x32_bf16 v[100:103], v[128:131], v[198:201], v[100:103]
	v_mfma_f32_16x16x32_bf16 v[100:103], v[142:145], v[202:205], v[100:103]
	s_setprio 0
	s_add_i32 s50, s72, s14
	s_mov_b32 m0, s50
	ds_read_b128 v[174:177], v153 offset:16384
	ds_read_b128 v[178:181], v153 offset:17408
	ds_read_b128 v[182:185], v153 offset:18432
	ds_read_b128 v[186:189], v153 offset:19456
	ds_read_b128 v[190:193], v153 offset:20480
	ds_read_b128 v[194:197], v153 offset:21504
	ds_read_b128 v[198:201], v153 offset:22528
	ds_read_b128 v[202:205], v153 offset:23552
	global_load_lds_dwordx4 v134, s[78:79]
	s_add_i32 m0, s50, 0x2000
	s_add_i32 s50, s73, s14
	s_add_u32 s98, s78, s6
	s_addc_u32 s99, s79, s7
	global_load_lds_dwordx4 v134, s[98:99]
	s_mov_b32 m0, s50
	s_nop 0
	s_add_u32 s98, s78, s8
	s_addc_u32 s99, s79, s9
	global_load_lds_dwordx4 v134, s[98:99]
	s_add_i32 m0, s50, 0x2000
	s_nop 0
	s_add_u32 s98, s78, s10
	s_addc_u32 s99, s79, s11
	global_load_lds_dwordx4 v134, s[98:99]
	s_mov_b32 m0, s20
	s_nop 0
	global_load_lds_dwordx4 v132, s[76:77]
	s_mov_b32 m0, s21
	s_nop 0
	s_add_u32 s98, s76, s6
	s_addc_u32 s99, s77, s7
	global_load_lds_dwordx4 v132, s[98:99]
	s_waitcnt vmcnt(8)
	s_waitcnt lgkmcnt(0)
	s_barrier
	s_setprio 1
	s_waitcnt lgkmcnt(0)
	v_mfma_f32_16x16x32_bf16 v[60:63], v[128:131], v[174:177], v[60:63]
	v_mfma_f32_16x16x32_bf16 v[60:63], v[142:145], v[178:181], v[60:63]
	v_mfma_f32_16x16x32_bf16 v[56:59], v[146:149], v[174:177], v[56:59]
	v_mfma_f32_16x16x32_bf16 v[56:59], v[154:157], v[178:181], v[56:59]
	v_mfma_f32_16x16x32_bf16 v[28:31], v[158:161], v[174:177], v[28:31]
	v_mfma_f32_16x16x32_bf16 v[28:31], v[162:165], v[178:181], v[28:31]
	v_mfma_f32_16x16x32_bf16 v[24:27], v[166:169], v[174:177], v[24:27]
	v_mfma_f32_16x16x32_bf16 v[24:27], v[170:173], v[178:181], v[24:27]
	v_mfma_f32_16x16x32_bf16 v[16:19], v[166:169], v[182:185], v[16:19]
	v_mfma_f32_16x16x32_bf16 v[16:19], v[170:173], v[186:189], v[16:19]
	v_mfma_f32_16x16x32_bf16 v[20:23], v[158:161], v[182:185], v[20:23]
	v_mfma_f32_16x16x32_bf16 v[20:23], v[162:165], v[186:189], v[20:23]
	v_mfma_f32_16x16x32_bf16 v[48:51], v[146:149], v[182:185], v[48:51]
	v_mfma_f32_16x16x32_bf16 v[48:51], v[154:157], v[186:189], v[48:51]
	v_mfma_f32_16x16x32_bf16 v[52:55], v[128:131], v[182:185], v[52:55]
	v_mfma_f32_16x16x32_bf16 v[52:55], v[142:145], v[186:189], v[52:55]
	s_setprio 0
	s_setprio 1
	v_mfma_f32_16x16x32_bf16 v[44:47], v[128:131], v[190:193], v[44:47]
	v_mfma_f32_16x16x32_bf16 v[44:47], v[142:145], v[194:197], v[44:47]
	v_mfma_f32_16x16x32_bf16 v[40:43], v[146:149], v[190:193], v[40:43]
	v_mfma_f32_16x16x32_bf16 v[40:43], v[154:157], v[194:197], v[40:43]
	v_mfma_f32_16x16x32_bf16 v[12:15], v[158:161], v[190:193], v[12:15]
	v_mfma_f32_16x16x32_bf16 v[12:15], v[162:165], v[194:197], v[12:15]
	v_mfma_f32_16x16x32_bf16 v[8:11], v[166:169], v[190:193], v[8:11]
	v_mfma_f32_16x16x32_bf16 v[8:11], v[170:173], v[194:197], v[8:11]
	s_setprio 2
	s_barrier
	v_mfma_f32_16x16x32_bf16 v[0:3], v[166:169], v[198:201], v[0:3]
	v_mfma_f32_16x16x32_bf16 v[0:3], v[170:173], v[202:205], v[0:3]
	v_mfma_f32_16x16x32_bf16 v[4:7], v[158:161], v[198:201], v[4:7]
	v_mfma_f32_16x16x32_bf16 v[4:7], v[162:165], v[202:205], v[4:7]
	v_mfma_f32_16x16x32_bf16 v[32:35], v[146:149], v[198:201], v[32:35]
	v_mfma_f32_16x16x32_bf16 v[32:35], v[154:157], v[202:205], v[32:35]
	v_mfma_f32_16x16x32_bf16 v[36:39], v[128:131], v[198:201], v[36:39]
	v_mfma_f32_16x16x32_bf16 v[36:39], v[142:145], v[202:205], v[36:39]
	s_setprio 0
	s_add_i32 s50, 0, 0x18000
	s_add_i32 s51, 0, 0x1c000
	v_add_u32_e32 v154, s50, v150
	v_add_u32_e32 v170, s51, v150
	ds_read_b128 v[128:131], v154
	ds_read_b128 v[142:145], v154 offset:1024
	ds_read_b128 v[146:149], v154 offset:2048
	ds_read_b128 v[154:157], v154 offset:3072
	ds_read_b128 v[158:161], v170
	ds_read_b128 v[162:165], v170 offset:1024
	ds_read_b128 v[166:169], v170 offset:2048
	ds_read_b128 v[170:173], v170 offset:3072
	s_mov_b32 m0, s33
	ds_read_b128 v[174:177], v153 offset:32768
	ds_read_b128 v[178:181], v153 offset:33792
	ds_read_b128 v[182:185], v153 offset:34816
	ds_read_b128 v[186:189], v153 offset:35840
	ds_read_b128 v[190:193], v153 offset:36864
	ds_read_b128 v[194:197], v153 offset:37888
	ds_read_b128 v[198:201], v153 offset:38912
	ds_read_b128 v[202:205], v153 offset:39936
	s_add_u32 s98, s76, s8
	s_addc_u32 s99, s77, s9
	global_load_lds_dwordx4 v132, s[98:99]
	s_mov_b32 m0, s64
	s_nop 0
	s_add_u32 s98, s76, s10
	s_addc_u32 s99, s77, s11
	global_load_lds_dwordx4 v132, s[98:99]
	s_waitcnt vmcnt(8)
	s_waitcnt lgkmcnt(0)
	s_barrier
	s_setprio 1
	s_waitcnt lgkmcnt(0)
	v_mfma_f32_16x16x32_bf16 v[124:127], v[128:131], v[174:177], v[124:127]
	v_mfma_f32_16x16x32_bf16 v[124:127], v[142:145], v[178:181], v[124:127]
	v_mfma_f32_16x16x32_bf16 v[120:123], v[146:149], v[174:177], v[120:123]
	v_mfma_f32_16x16x32_bf16 v[120:123], v[154:157], v[178:181], v[120:123]
	v_mfma_f32_16x16x32_bf16 v[92:95], v[158:161], v[174:177], v[92:95]
	v_mfma_f32_16x16x32_bf16 v[92:95], v[162:165], v[178:181], v[92:95]
	v_mfma_f32_16x16x32_bf16 v[88:91], v[166:169], v[174:177], v[88:91]
	v_mfma_f32_16x16x32_bf16 v[88:91], v[170:173], v[178:181], v[88:91]
	v_mfma_f32_16x16x32_bf16 v[80:83], v[166:169], v[182:185], v[80:83]
	v_mfma_f32_16x16x32_bf16 v[80:83], v[170:173], v[186:189], v[80:83]
	v_mfma_f32_16x16x32_bf16 v[84:87], v[158:161], v[182:185], v[84:87]
	v_mfma_f32_16x16x32_bf16 v[84:87], v[162:165], v[186:189], v[84:87]
	v_mfma_f32_16x16x32_bf16 v[112:115], v[146:149], v[182:185], v[112:115]
	v_mfma_f32_16x16x32_bf16 v[112:115], v[154:157], v[186:189], v[112:115]
	v_mfma_f32_16x16x32_bf16 v[116:119], v[128:131], v[182:185], v[116:119]
	v_mfma_f32_16x16x32_bf16 v[116:119], v[142:145], v[186:189], v[116:119]
	s_setprio 0
	s_setprio 1
	v_mfma_f32_16x16x32_bf16 v[108:111], v[128:131], v[190:193], v[108:111]
	v_mfma_f32_16x16x32_bf16 v[108:111], v[142:145], v[194:197], v[108:111]
	v_mfma_f32_16x16x32_bf16 v[104:107], v[146:149], v[190:193], v[104:107]
	v_mfma_f32_16x16x32_bf16 v[104:107], v[154:157], v[194:197], v[104:107]
	v_mfma_f32_16x16x32_bf16 v[76:79], v[158:161], v[190:193], v[76:79]
	v_mfma_f32_16x16x32_bf16 v[76:79], v[162:165], v[194:197], v[76:79]
	v_mfma_f32_16x16x32_bf16 v[72:75], v[166:169], v[190:193], v[72:75]
	v_mfma_f32_16x16x32_bf16 v[72:75], v[170:173], v[194:197], v[72:75]
	s_setprio 2
	s_barrier
	v_mfma_f32_16x16x32_bf16 v[64:67], v[166:169], v[198:201], v[64:67]
	v_mfma_f32_16x16x32_bf16 v[64:67], v[170:173], v[202:205], v[64:67]
	v_mfma_f32_16x16x32_bf16 v[68:71], v[158:161], v[198:201], v[68:71]
	v_mfma_f32_16x16x32_bf16 v[68:71], v[162:165], v[202:205], v[68:71]
	v_mfma_f32_16x16x32_bf16 v[96:99], v[146:149], v[198:201], v[96:99]
	v_mfma_f32_16x16x32_bf16 v[96:99], v[154:157], v[202:205], v[96:99]
	v_mfma_f32_16x16x32_bf16 v[100:103], v[128:131], v[198:201], v[100:103]
	v_mfma_f32_16x16x32_bf16 v[100:103], v[142:145], v[202:205], v[100:103]
	s_setprio 0
	s_add_i32 s50, s50, s14
	s_mov_b32 m0, s50
	ds_read_b128 v[174:177], v153 offset:49152
	ds_read_b128 v[178:181], v153 offset:50176
	ds_read_b128 v[182:185], v153 offset:51200
	ds_read_b128 v[186:189], v153 offset:52224
	ds_read_b128 v[190:193], v153 offset:53248
	ds_read_b128 v[194:197], v153 offset:54272
	ds_read_b128 v[198:201], v153 offset:55296
	ds_read_b128 v[202:205], v153 offset:56320
	s_add_u32 s98, s78, s24
	s_addc_u32 s99, s79, s25
	global_load_lds_dwordx4 v134, s[98:99]
	s_add_i32 m0, s50, 0x2000
	s_add_i32 s50, s51, s14
	s_add_u32 s98, s78, s34
	s_addc_u32 s99, s79, s35
	global_load_lds_dwordx4 v134, s[98:99]
	s_mov_b32 m0, s50
	s_add_u32 s98, s78, s36
	s_addc_u32 s99, s79, s37
	global_load_lds_dwordx4 v134, s[98:99]
	s_add_i32 m0, s50, 0x2000
	s_nop 0
	s_add_u32 s98, s78, s38
	s_addc_u32 s99, s79, s39
	global_load_lds_dwordx4 v134, s[98:99]
	s_mov_b32 m0, s66
	s_nop 0
	s_add_u32 s98, s76, s24
	s_addc_u32 s99, s77, s25
	global_load_lds_dwordx4 v132, s[98:99]
	s_mov_b32 m0, s67
	s_nop 0
	s_add_u32 s98, s76, s34
	s_addc_u32 s99, s77, s35
	global_load_lds_dwordx4 v132, s[98:99]
	s_waitcnt vmcnt(8)
	s_waitcnt lgkmcnt(0)
	s_barrier
	s_setprio 1
	s_waitcnt lgkmcnt(0)
	v_mfma_f32_16x16x32_bf16 v[60:63], v[128:131], v[174:177], v[60:63]
	v_mfma_f32_16x16x32_bf16 v[60:63], v[142:145], v[178:181], v[60:63]
	v_mfma_f32_16x16x32_bf16 v[56:59], v[146:149], v[174:177], v[56:59]
	v_mfma_f32_16x16x32_bf16 v[56:59], v[154:157], v[178:181], v[56:59]
	v_mfma_f32_16x16x32_bf16 v[28:31], v[158:161], v[174:177], v[28:31]
	v_mfma_f32_16x16x32_bf16 v[28:31], v[162:165], v[178:181], v[28:31]
	v_mfma_f32_16x16x32_bf16 v[24:27], v[166:169], v[174:177], v[24:27]
	v_mfma_f32_16x16x32_bf16 v[24:27], v[170:173], v[178:181], v[24:27]
	v_mfma_f32_16x16x32_bf16 v[16:19], v[166:169], v[182:185], v[16:19]
	v_mfma_f32_16x16x32_bf16 v[16:19], v[170:173], v[186:189], v[16:19]
	v_mfma_f32_16x16x32_bf16 v[20:23], v[158:161], v[182:185], v[20:23]
	v_mfma_f32_16x16x32_bf16 v[20:23], v[162:165], v[186:189], v[20:23]
	v_mfma_f32_16x16x32_bf16 v[48:51], v[146:149], v[182:185], v[48:51]
	v_mfma_f32_16x16x32_bf16 v[48:51], v[154:157], v[186:189], v[48:51]
	v_mfma_f32_16x16x32_bf16 v[52:55], v[128:131], v[182:185], v[52:55]
	v_mfma_f32_16x16x32_bf16 v[52:55], v[142:145], v[186:189], v[52:55]
	s_setprio 0
	s_setprio 1
	v_mfma_f32_16x16x32_bf16 v[44:47], v[128:131], v[190:193], v[44:47]
	v_mfma_f32_16x16x32_bf16 v[44:47], v[142:145], v[194:197], v[44:47]
	v_mfma_f32_16x16x32_bf16 v[40:43], v[146:149], v[190:193], v[40:43]
	v_mfma_f32_16x16x32_bf16 v[40:43], v[154:157], v[194:197], v[40:43]
	v_mfma_f32_16x16x32_bf16 v[12:15], v[158:161], v[190:193], v[12:15]
	v_mfma_f32_16x16x32_bf16 v[12:15], v[162:165], v[194:197], v[12:15]
	v_mfma_f32_16x16x32_bf16 v[8:11], v[166:169], v[190:193], v[8:11]
	v_mfma_f32_16x16x32_bf16 v[8:11], v[170:173], v[194:197], v[8:11]
	s_setprio 2
	s_barrier
	v_mfma_f32_16x16x32_bf16 v[0:3], v[166:169], v[198:201], v[0:3]
	v_mfma_f32_16x16x32_bf16 v[0:3], v[170:173], v[202:205], v[0:3]
	v_mfma_f32_16x16x32_bf16 v[4:7], v[158:161], v[198:201], v[4:7]
	v_mfma_f32_16x16x32_bf16 v[4:7], v[162:165], v[202:205], v[4:7]
	v_mfma_f32_16x16x32_bf16 v[32:35], v[146:149], v[198:201], v[32:35]
	v_mfma_f32_16x16x32_bf16 v[32:35], v[154:157], v[202:205], v[32:35]
	v_mfma_f32_16x16x32_bf16 v[36:39], v[128:131], v[198:201], v[36:39]
	v_mfma_f32_16x16x32_bf16 v[36:39], v[142:145], v[202:205], v[36:39]
	s_setprio 0
	s_add_i32 s62, s62, 2
	s_add_u32 s74, s74, 0x100
	s_addc_u32 s75, s75, 0
	s_add_u32 s60, s60, 0x100
	s_addc_u32 s61, s61, 0
	s_cmp_gt_u32 s62, 61
	s_cbranch_scc0 .LBB0_627
	s_and_b64 vcc, exec, s[40:41]
	s_cbranch_vccz .LBB0_630
	s_barrier

.Lcm4_skip:
.LBB0_800:
	ds_read_b128 v[128:131], v187
	ds_read_b128 v[132:135], v187 offset:1024
	ds_read_b128 v[136:139], v187 offset:2048
	ds_read_b128 v[140:143], v187 offset:3072
	ds_read_b128 v[144:147], v188
	ds_read_b128 v[148:151], v188 offset:1024
	ds_read_b128 v[152:155], v188 offset:2048
	ds_read_b128 v[156:159], v188 offset:3072
	s_add_u32 s9, s6, 0xfff80080
	s_addc_u32 s50, s7, -1
	s_cmp_eq_u32 s8, 28
	s_cselect_b32 vcc_hi, s5, s50
	s_cselect_b32 vcc_lo, s10, s9
	s_cselect_b32 s51, s11, s78
	s_cselect_b32 s50, s73, s75
	s_add_i32 m0, s65, 0xc000
	ds_read_b128 v[160:163], v189
	ds_read_b128 v[164:167], v189 offset:1024
	ds_read_b128 v[168:171], v189 offset:2048
	ds_read_b128 v[192:195], v189 offset:3072
	ds_read_b128 v[196:199], v189 offset:4096
	ds_read_b128 v[200:203], v189 offset:5120
	ds_read_b128 v[204:207], v189 offset:6144
	ds_read_b128 v[208:211], v189 offset:7168
	global_load_lds_dwordx4 v178, s[6:7]
	s_add_i32 m0, s65, 0xe000
	s_nop 0
	s_add_u32 s98, s6, s36
	s_addc_u32 s99, s7, s37
	global_load_lds_dwordx4 v178, s[98:99]
	s_waitcnt vmcnt(8)
	s_waitcnt lgkmcnt(0)
	s_barrier
	s_setprio 1
	s_waitcnt lgkmcnt(0)
	v_mfma_i32_16x16x64_i8 v[84:87], v[128:131], v[160:163], v[84:87]
	v_mfma_i32_16x16x64_i8 v[84:87], v[132:135], v[164:167], v[84:87]
	v_mfma_i32_16x16x64_i8 v[16:19], v[136:139], v[160:163], v[16:19]
	v_mfma_i32_16x16x64_i8 v[16:19], v[140:143], v[164:167], v[16:19]
	v_mfma_i32_16x16x64_i8 v[124:127], v[144:147], v[160:163], v[124:127]
	v_mfma_i32_16x16x64_i8 v[124:127], v[148:151], v[164:167], v[124:127]
	v_mfma_i32_16x16x64_i8 v[68:71], v[152:155], v[160:163], v[68:71]
	v_mfma_i32_16x16x64_i8 v[68:71], v[156:159], v[164:167], v[68:71]
	v_mfma_i32_16x16x64_i8 v[72:75], v[152:155], v[168:171], v[72:75]
	v_mfma_i32_16x16x64_i8 v[72:75], v[156:159], v[192:195], v[72:75]
	v_mfma_i32_16x16x64_i8 v[120:123], v[144:147], v[168:171], v[120:123]
	v_mfma_i32_16x16x64_i8 v[120:123], v[148:151], v[192:195], v[120:123]
	v_mfma_i32_16x16x64_i8 v[20:23], v[136:139], v[168:171], v[20:23]
	v_mfma_i32_16x16x64_i8 v[20:23], v[140:143], v[192:195], v[20:23]
	v_mfma_i32_16x16x64_i8 v[88:91], v[128:131], v[168:171], v[88:91]
	v_mfma_i32_16x16x64_i8 v[88:91], v[132:135], v[192:195], v[88:91]
	s_setprio 0
	s_setprio 1
	v_mfma_i32_16x16x64_i8 v[92:95], v[128:131], v[196:199], v[92:95]
	v_mfma_i32_16x16x64_i8 v[92:95], v[132:135], v[200:203], v[92:95]
	v_mfma_i32_16x16x64_i8 v[24:27], v[136:139], v[196:199], v[24:27]
	v_mfma_i32_16x16x64_i8 v[24:27], v[140:143], v[200:203], v[24:27]
	v_mfma_i32_16x16x64_i8 v[116:119], v[144:147], v[196:199], v[116:119]
	v_mfma_i32_16x16x64_i8 v[116:119], v[148:151], v[200:203], v[116:119]
	v_mfma_i32_16x16x64_i8 v[80:83], v[152:155], v[196:199], v[80:83]
	v_mfma_i32_16x16x64_i8 v[80:83], v[156:159], v[200:203], v[80:83]
	s_setprio 2
	s_barrier
	v_mfma_i32_16x16x64_i8 v[60:63], v[152:155], v[204:207], v[60:63]
	v_mfma_i32_16x16x64_i8 v[60:63], v[156:159], v[208:211], v[60:63]
	v_mfma_i32_16x16x64_i8 v[112:115], v[144:147], v[204:207], v[112:115]
	v_mfma_i32_16x16x64_i8 v[112:115], v[148:151], v[208:211], v[112:115]
	v_mfma_i32_16x16x64_i8 v[28:31], v[136:139], v[204:207], v[28:31]
	v_mfma_i32_16x16x64_i8 v[28:31], v[140:143], v[208:211], v[28:31]
	v_mfma_i32_16x16x64_i8 v[96:99], v[128:131], v[204:207], v[96:99]
	v_mfma_i32_16x16x64_i8 v[96:99], v[132:135], v[208:211], v[96:99]
	s_setprio 0
	s_add_i32 s9, s80, s33
	s_mov_b64 s[100:101], s[50:51]
	s_mov_b32 m0, s9
	ds_read_b128 v[160:163], v189 offset:16384
	ds_read_b128 v[164:167], v189 offset:17408
	ds_read_b128 v[168:171], v189 offset:18432
	ds_read_b128 v[192:195], v189 offset:19456
	ds_read_b128 v[196:199], v189 offset:20480
	ds_read_b128 v[200:203], v189 offset:21504
	ds_read_b128 v[204:207], v189 offset:22528
	ds_read_b128 v[208:211], v189 offset:23552
	global_load_lds_dwordx4 v174, s[50:51]
	s_add_i32 m0, s9, 0x2000
	s_add_i32 s9, s81, s33
	s_add_u32 s98, s50, s36
	s_addc_u32 s99, s51, s37
	global_load_lds_dwordx4 v174, s[98:99]
	s_mov_b32 m0, s9
	s_nop 0
	s_add_u32 s98, s50, s38
	s_addc_u32 s99, s51, s39
	global_load_lds_dwordx4 v174, s[98:99]
	s_add_i32 m0, s9, 0x2000
	s_nop 0
	s_add_u32 s98, s50, s40
	s_addc_u32 s99, s51, s41
	global_load_lds_dwordx4 v174, s[98:99]
	s_mov_b32 m0, s65
	s_nop 0
	global_load_lds_dwordx4 v172, vcc
	s_mov_b32 m0, s67
	s_nop 0
	s_add_u32 s98, vcc_lo, s36
	s_addc_u32 s99, vcc_hi, s37
	global_load_lds_dwordx4 v172, s[98:99]
	s_waitcnt vmcnt(8)
	s_waitcnt lgkmcnt(0)
	s_barrier
	s_setprio 1
	s_waitcnt lgkmcnt(0)
	v_mfma_i32_16x16x64_i8 v[48:51], v[128:131], v[160:163], v[48:51]
	v_mfma_i32_16x16x64_i8 v[48:51], v[132:135], v[164:167], v[48:51]
	v_mfma_i32_16x16x64_i8 v[0:3], v[136:139], v[160:163], v[0:3]
	v_mfma_i32_16x16x64_i8 v[0:3], v[140:143], v[164:167], v[0:3]
	v_mfma_i32_16x16x64_i8 v[108:111], v[144:147], v[160:163], v[108:111]
	v_mfma_i32_16x16x64_i8 v[108:111], v[148:151], v[164:167], v[108:111]
	v_mfma_i32_16x16x64_i8 v[44:47], v[152:155], v[160:163], v[44:47]
	v_mfma_i32_16x16x64_i8 v[44:47], v[156:159], v[164:167], v[44:47]
	v_mfma_i32_16x16x64_i8 v[40:43], v[152:155], v[168:171], v[40:43]
	v_mfma_i32_16x16x64_i8 v[40:43], v[156:159], v[192:195], v[40:43]
	v_mfma_i32_16x16x64_i8 v[104:107], v[144:147], v[168:171], v[104:107]
	v_mfma_i32_16x16x64_i8 v[104:107], v[148:151], v[192:195], v[104:107]
	v_mfma_i32_16x16x64_i8 v[4:7], v[136:139], v[168:171], v[4:7]
	v_mfma_i32_16x16x64_i8 v[4:7], v[140:143], v[192:195], v[4:7]
	v_mfma_i32_16x16x64_i8 v[52:55], v[128:131], v[168:171], v[52:55]
	v_mfma_i32_16x16x64_i8 v[52:55], v[132:135], v[192:195], v[52:55]
	s_setprio 0
	s_setprio 1
	v_mfma_i32_16x16x64_i8 v[56:59], v[128:131], v[196:199], v[56:59]
	v_mfma_i32_16x16x64_i8 v[56:59], v[132:135], v[200:203], v[56:59]
	v_mfma_i32_16x16x64_i8 v[8:11], v[136:139], v[196:199], v[8:11]
	v_mfma_i32_16x16x64_i8 v[8:11], v[140:143], v[200:203], v[8:11]
	v_mfma_i32_16x16x64_i8 v[100:103], v[144:147], v[196:199], v[100:103]
	v_mfma_i32_16x16x64_i8 v[100:103], v[148:151], v[200:203], v[100:103]
	v_mfma_i32_16x16x64_i8 v[32:35], v[152:155], v[196:199], v[32:35]
	v_mfma_i32_16x16x64_i8 v[32:35], v[156:159], v[200:203], v[32:35]
	s_setprio 2
	s_barrier
	v_mfma_i32_16x16x64_i8 v[36:39], v[152:155], v[204:207], v[36:39]
	v_mfma_i32_16x16x64_i8 v[36:39], v[156:159], v[208:211], v[36:39]
	v_mfma_i32_16x16x64_i8 v[76:79], v[144:147], v[204:207], v[76:79]
	v_mfma_i32_16x16x64_i8 v[76:79], v[148:151], v[208:211], v[76:79]
	v_mfma_i32_16x16x64_i8 v[12:15], v[136:139], v[204:207], v[12:15]
	v_mfma_i32_16x16x64_i8 v[12:15], v[140:143], v[208:211], v[12:15]
	v_mfma_i32_16x16x64_i8 v[64:67], v[128:131], v[204:207], v[64:67]
	v_mfma_i32_16x16x64_i8 v[64:67], v[132:135], v[208:211], v[64:67]
	s_setprio 0
	s_add_i32 s9, 0, 0x18000
	s_add_i32 s50, 0, 0x1c000
	v_add_u32_e32 v140, s9, v186
	v_add_u32_e32 v156, s50, v186
	ds_read_b128 v[128:131], v140
	ds_read_b128 v[132:135], v140 offset:1024
	ds_read_b128 v[136:139], v140 offset:2048
	ds_read_b128 v[140:143], v140 offset:3072
	ds_read_b128 v[144:147], v156
	ds_read_b128 v[148:151], v156 offset:1024
	ds_read_b128 v[152:155], v156 offset:2048
	ds_read_b128 v[156:159], v156 offset:3072
	s_mov_b32 m0, s71
	ds_read_b128 v[160:163], v189 offset:32768
	ds_read_b128 v[164:167], v189 offset:33792
	ds_read_b128 v[168:171], v189 offset:34816
	ds_read_b128 v[192:195], v189 offset:35840
	ds_read_b128 v[196:199], v189 offset:36864
	ds_read_b128 v[200:203], v189 offset:37888
	ds_read_b128 v[204:207], v189 offset:38912
	ds_read_b128 v[208:211], v189 offset:39936
	s_add_u32 s98, vcc_lo, s38
	s_addc_u32 s99, vcc_hi, s39
	global_load_lds_dwordx4 v172, s[98:99]
	s_mov_b32 m0, s82
	s_nop 0
	s_add_u32 s98, vcc_lo, s40
	s_addc_u32 s99, vcc_hi, s41
	global_load_lds_dwordx4 v172, s[98:99]
	s_waitcnt vmcnt(8)
	s_waitcnt lgkmcnt(0)
	s_barrier
	s_setprio 1
	s_waitcnt lgkmcnt(0)
	v_mfma_i32_16x16x64_i8 v[84:87], v[128:131], v[160:163], v[84:87]
	v_mfma_i32_16x16x64_i8 v[84:87], v[132:135], v[164:167], v[84:87]
	v_mfma_i32_16x16x64_i8 v[16:19], v[136:139], v[160:163], v[16:19]
	v_mfma_i32_16x16x64_i8 v[16:19], v[140:143], v[164:167], v[16:19]
	v_mfma_i32_16x16x64_i8 v[124:127], v[144:147], v[160:163], v[124:127]
	v_mfma_i32_16x16x64_i8 v[124:127], v[148:151], v[164:167], v[124:127]
	v_mfma_i32_16x16x64_i8 v[68:71], v[152:155], v[160:163], v[68:71]
	v_mfma_i32_16x16x64_i8 v[68:71], v[156:159], v[164:167], v[68:71]
	v_mfma_i32_16x16x64_i8 v[72:75], v[152:155], v[168:171], v[72:75]
	v_mfma_i32_16x16x64_i8 v[72:75], v[156:159], v[192:195], v[72:75]
	v_mfma_i32_16x16x64_i8 v[120:123], v[144:147], v[168:171], v[120:123]
	v_mfma_i32_16x16x64_i8 v[120:123], v[148:151], v[192:195], v[120:123]
	v_mfma_i32_16x16x64_i8 v[20:23], v[136:139], v[168:171], v[20:23]
	v_mfma_i32_16x16x64_i8 v[20:23], v[140:143], v[192:195], v[20:23]
	v_mfma_i32_16x16x64_i8 v[88:91], v[128:131], v[168:171], v[88:91]
	v_mfma_i32_16x16x64_i8 v[88:91], v[132:135], v[192:195], v[88:91]
	s_setprio 0
	s_setprio 1
	v_mfma_i32_16x16x64_i8 v[92:95], v[128:131], v[196:199], v[92:95]
	v_mfma_i32_16x16x64_i8 v[92:95], v[132:135], v[200:203], v[92:95]
	v_mfma_i32_16x16x64_i8 v[24:27], v[136:139], v[196:199], v[24:27]
	v_mfma_i32_16x16x64_i8 v[24:27], v[140:143], v[200:203], v[24:27]
	v_mfma_i32_16x16x64_i8 v[116:119], v[144:147], v[196:199], v[116:119]
	v_mfma_i32_16x16x64_i8 v[116:119], v[148:151], v[200:203], v[116:119]
	v_mfma_i32_16x16x64_i8 v[80:83], v[152:155], v[196:199], v[80:83]
	v_mfma_i32_16x16x64_i8 v[80:83], v[156:159], v[200:203], v[80:83]
	s_setprio 2
	s_barrier
	v_mfma_i32_16x16x64_i8 v[60:63], v[152:155], v[204:207], v[60:63]
	v_mfma_i32_16x16x64_i8 v[60:63], v[156:159], v[208:211], v[60:63]
	v_mfma_i32_16x16x64_i8 v[112:115], v[144:147], v[204:207], v[112:115]
	v_mfma_i32_16x16x64_i8 v[112:115], v[148:151], v[208:211], v[112:115]
	v_mfma_i32_16x16x64_i8 v[28:31], v[136:139], v[204:207], v[28:31]
	v_mfma_i32_16x16x64_i8 v[28:31], v[140:143], v[208:211], v[28:31]
	v_mfma_i32_16x16x64_i8 v[96:99], v[128:131], v[204:207], v[96:99]
	v_mfma_i32_16x16x64_i8 v[96:99], v[132:135], v[208:211], v[96:99]
	s_setprio 0
	s_add_i32 s9, s9, s33
	s_mov_b32 m0, s9
	ds_read_b128 v[160:163], v189 offset:49152
	ds_read_b128 v[164:167], v189 offset:50176
	ds_read_b128 v[168:171], v189 offset:51200
	ds_read_b128 v[192:195], v189 offset:52224
	ds_read_b128 v[196:199], v189 offset:53248
	ds_read_b128 v[200:203], v189 offset:54272
	ds_read_b128 v[204:207], v189 offset:55296
	ds_read_b128 v[208:211], v189 offset:56320
	s_add_u32 s98, s100, s44
	s_addc_u32 s99, s101, s45
	global_load_lds_dwordx4 v174, s[98:99]
	s_add_i32 m0, s9, 0x2000
	s_add_i32 s9, s50, s33
	s_add_u32 s98, s100, s46
	s_addc_u32 s99, s101, s47
	global_load_lds_dwordx4 v174, s[98:99]
	s_mov_b32 m0, s9
	s_add_u32 s98, s100, s48
	s_addc_u32 s99, s101, s49
	global_load_lds_dwordx4 v174, s[98:99]
	s_add_i32 m0, s9, 0x2000
	s_nop 0
	s_add_u32 s98, s100, s52
	s_addc_u32 s99, s101, s53
	global_load_lds_dwordx4 v174, s[98:99]
	s_mov_b32 m0, s90
	s_nop 0
	s_add_u32 s98, vcc_lo, s44
	s_addc_u32 s99, vcc_hi, s45
	global_load_lds_dwordx4 v172, s[98:99]
	s_mov_b32 m0, s91
	s_nop 0
	s_add_u32 s98, vcc_lo, s46
	s_addc_u32 s99, vcc_hi, s47
	global_load_lds_dwordx4 v172, s[98:99]
	s_waitcnt vmcnt(8)
	s_waitcnt lgkmcnt(0)
	s_barrier
	s_setprio 1
	s_waitcnt lgkmcnt(0)
	v_mfma_i32_16x16x64_i8 v[48:51], v[128:131], v[160:163], v[48:51]
	v_mfma_i32_16x16x64_i8 v[48:51], v[132:135], v[164:167], v[48:51]
	v_mfma_i32_16x16x64_i8 v[0:3], v[136:139], v[160:163], v[0:3]
	v_mfma_i32_16x16x64_i8 v[0:3], v[140:143], v[164:167], v[0:3]
	v_mfma_i32_16x16x64_i8 v[108:111], v[144:147], v[160:163], v[108:111]
	v_mfma_i32_16x16x64_i8 v[108:111], v[148:151], v[164:167], v[108:111]
	v_mfma_i32_16x16x64_i8 v[44:47], v[152:155], v[160:163], v[44:47]
	v_mfma_i32_16x16x64_i8 v[44:47], v[156:159], v[164:167], v[44:47]
	v_mfma_i32_16x16x64_i8 v[40:43], v[152:155], v[168:171], v[40:43]
	v_mfma_i32_16x16x64_i8 v[40:43], v[156:159], v[192:195], v[40:43]
	v_mfma_i32_16x16x64_i8 v[104:107], v[144:147], v[168:171], v[104:107]
	v_mfma_i32_16x16x64_i8 v[104:107], v[148:151], v[192:195], v[104:107]
	v_mfma_i32_16x16x64_i8 v[4:7], v[136:139], v[168:171], v[4:7]
	v_mfma_i32_16x16x64_i8 v[4:7], v[140:143], v[192:195], v[4:7]
	v_mfma_i32_16x16x64_i8 v[52:55], v[128:131], v[168:171], v[52:55]
	v_mfma_i32_16x16x64_i8 v[52:55], v[132:135], v[192:195], v[52:55]
	s_setprio 0
	s_setprio 1
	v_mfma_i32_16x16x64_i8 v[56:59], v[128:131], v[196:199], v[56:59]
	v_mfma_i32_16x16x64_i8 v[56:59], v[132:135], v[200:203], v[56:59]
	v_mfma_i32_16x16x64_i8 v[8:11], v[136:139], v[196:199], v[8:11]
	v_mfma_i32_16x16x64_i8 v[8:11], v[140:143], v[200:203], v[8:11]
	v_mfma_i32_16x16x64_i8 v[100:103], v[144:147], v[196:199], v[100:103]
	v_mfma_i32_16x16x64_i8 v[100:103], v[148:151], v[200:203], v[100:103]
	v_mfma_i32_16x16x64_i8 v[32:35], v[152:155], v[196:199], v[32:35]
	v_mfma_i32_16x16x64_i8 v[32:35], v[156:159], v[200:203], v[32:35]
	s_setprio 2
	s_barrier
	v_mfma_i32_16x16x64_i8 v[36:39], v[152:155], v[204:207], v[36:39]
	v_mfma_i32_16x16x64_i8 v[36:39], v[156:159], v[208:211], v[36:39]
	v_mfma_i32_16x16x64_i8 v[76:79], v[144:147], v[204:207], v[76:79]
	v_mfma_i32_16x16x64_i8 v[76:79], v[148:151], v[208:211], v[76:79]
	v_mfma_i32_16x16x64_i8 v[12:15], v[136:139], v[204:207], v[12:15]
	v_mfma_i32_16x16x64_i8 v[12:15], v[140:143], v[208:211], v[12:15]
	v_mfma_i32_16x16x64_i8 v[64:67], v[128:131], v[204:207], v[64:67]
	v_mfma_i32_16x16x64_i8 v[64:67], v[132:135], v[208:211], v[64:67]
	s_setprio 0
	s_add_i32 s8, s8, 2
	s_add_u32 s75, s75, 0x100
	s_addc_u32 s78, s78, 0
	s_add_u32 s6, s6, 0x100
	s_addc_u32 s7, s7, 0
	s_cmp_gt_u32 s8, 29
	s_cbranch_scc0 .LBB0_800
	s_and_b64 vcc, exec, s[54:55]
	s_cbranch_vccz .LBB0_803
	s_barrier

.LBB0_1034:
	ds_read_b128 v[138:141], v151
	ds_read_b128 v[142:145], v151 offset:1024
	ds_read_b128 v[146:149], v151 offset:2048
	ds_read_b128 v[154:157], v151 offset:3072
	ds_read_b128 v[158:161], v152
	ds_read_b128 v[162:165], v152 offset:1024
	ds_read_b128 v[166:169], v152 offset:2048
	ds_read_b128 v[170:173], v152 offset:3072
	s_add_u32 s47, s44, 0xffd50080
	s_addc_u32 s64, s45, -1
	s_cmpk_eq_i32 s46, 0xa8
	s_cselect_b32 s65, s5, s64
	s_cselect_b32 s64, s4, s47
	s_cselect_b32 s67, s43, s63
	s_cselect_b32 s66, s42, s62
	s_add_i32 m0, s25, 0xc000
	ds_read_b128 v[174:177], v153
	ds_read_b128 v[178:181], v153 offset:1024
	ds_read_b128 v[182:185], v153 offset:2048
	ds_read_b128 v[186:189], v153 offset:3072
	ds_read_b128 v[190:193], v153 offset:4096
	ds_read_b128 v[194:197], v153 offset:5120
	ds_read_b128 v[198:201], v153 offset:6144
	ds_read_b128 v[202:205], v153 offset:7168
	global_load_lds_dwordx4 v132, s[44:45]
	s_add_i32 m0, s25, 0xe000
	s_nop 0
	s_add_u32 s98, s44, s0
	s_addc_u32 s99, s45, s1
	global_load_lds_dwordx4 v132, s[98:99]
	s_waitcnt vmcnt(8)
	s_waitcnt lgkmcnt(0)
	s_barrier
	s_setprio 1
	s_waitcnt lgkmcnt(0)
	v_mfma_f32_16x16x32_bf16 v[124:127], v[138:141], v[174:177], v[124:127]
	v_mfma_f32_16x16x32_bf16 v[124:127], v[142:145], v[178:181], v[124:127]
	v_mfma_f32_16x16x32_bf16 v[120:123], v[146:149], v[174:177], v[120:123]
	v_mfma_f32_16x16x32_bf16 v[120:123], v[154:157], v[178:181], v[120:123]
	v_mfma_f32_16x16x32_bf16 v[92:95], v[158:161], v[174:177], v[92:95]
	v_mfma_f32_16x16x32_bf16 v[92:95], v[162:165], v[178:181], v[92:95]
	v_mfma_f32_16x16x32_bf16 v[88:91], v[166:169], v[174:177], v[88:91]
	v_mfma_f32_16x16x32_bf16 v[88:91], v[170:173], v[178:181], v[88:91]
	v_mfma_f32_16x16x32_bf16 v[80:83], v[166:169], v[182:185], v[80:83]
	v_mfma_f32_16x16x32_bf16 v[80:83], v[170:173], v[186:189], v[80:83]
	v_mfma_f32_16x16x32_bf16 v[84:87], v[158:161], v[182:185], v[84:87]
	v_mfma_f32_16x16x32_bf16 v[84:87], v[162:165], v[186:189], v[84:87]
	v_mfma_f32_16x16x32_bf16 v[112:115], v[146:149], v[182:185], v[112:115]
	v_mfma_f32_16x16x32_bf16 v[112:115], v[154:157], v[186:189], v[112:115]
	v_mfma_f32_16x16x32_bf16 v[116:119], v[138:141], v[182:185], v[116:119]
	v_mfma_f32_16x16x32_bf16 v[116:119], v[142:145], v[186:189], v[116:119]
	s_setprio 0
	s_setprio 1
	v_mfma_f32_16x16x32_bf16 v[108:111], v[138:141], v[190:193], v[108:111]
	v_mfma_f32_16x16x32_bf16 v[108:111], v[142:145], v[194:197], v[108:111]
	v_mfma_f32_16x16x32_bf16 v[104:107], v[146:149], v[190:193], v[104:107]
	v_mfma_f32_16x16x32_bf16 v[104:107], v[154:157], v[194:197], v[104:107]
	v_mfma_f32_16x16x32_bf16 v[76:79], v[158:161], v[190:193], v[76:79]
	v_mfma_f32_16x16x32_bf16 v[76:79], v[162:165], v[194:197], v[76:79]
	v_mfma_f32_16x16x32_bf16 v[72:75], v[166:169], v[190:193], v[72:75]
	v_mfma_f32_16x16x32_bf16 v[72:75], v[170:173], v[194:197], v[72:75]
	s_setprio 2
	s_barrier
	v_mfma_f32_16x16x32_bf16 v[64:67], v[166:169], v[198:201], v[64:67]
	v_mfma_f32_16x16x32_bf16 v[64:67], v[170:173], v[202:205], v[64:67]
	v_mfma_f32_16x16x32_bf16 v[68:71], v[158:161], v[198:201], v[68:71]
	v_mfma_f32_16x16x32_bf16 v[68:71], v[162:165], v[202:205], v[68:71]
	v_mfma_f32_16x16x32_bf16 v[96:99], v[146:149], v[198:201], v[96:99]
	v_mfma_f32_16x16x32_bf16 v[96:99], v[154:157], v[202:205], v[96:99]
	v_mfma_f32_16x16x32_bf16 v[100:103], v[138:141], v[198:201], v[100:103]
	v_mfma_f32_16x16x32_bf16 v[100:103], v[142:145], v[202:205], v[100:103]
	s_setprio 0
	s_add_i32 s47, s56, s24
	s_mov_b32 m0, s47
	ds_read_b128 v[174:177], v153 offset:16384
	ds_read_b128 v[178:181], v153 offset:17408
	ds_read_b128 v[182:185], v153 offset:18432
	ds_read_b128 v[186:189], v153 offset:19456
	ds_read_b128 v[190:193], v153 offset:20480
	ds_read_b128 v[194:197], v153 offset:21504
	ds_read_b128 v[198:201], v153 offset:22528
	ds_read_b128 v[202:205], v153 offset:23552
	global_load_lds_dwordx4 v130, s[66:67]
	s_add_i32 m0, s47, 0x2000
	s_add_i32 s47, s57, s24
	s_add_u32 s98, s66, s0
	s_addc_u32 s99, s67, s1
	global_load_lds_dwordx4 v130, s[98:99]
	s_mov_b32 m0, s47
	s_nop 0
	s_add_u32 s98, s66, s6
	s_addc_u32 s99, s67, s7
	global_load_lds_dwordx4 v130, s[98:99]
	s_add_i32 m0, s47, 0x2000
	s_nop 0
	s_add_u32 s98, s66, s8
	s_addc_u32 s99, s67, s9
	global_load_lds_dwordx4 v130, s[98:99]
	s_mov_b64 s[100:101], s[64:65]
	s_mov_b32 m0, s25
	s_nop 0
	global_load_lds_dwordx4 v128, s[64:65]
	s_mov_b32 m0, s33
	s_nop 0
	s_add_u32 s98, s64, s0
	s_addc_u32 s99, s65, s1
	global_load_lds_dwordx4 v128, s[98:99]
	s_waitcnt vmcnt(8)
	s_waitcnt lgkmcnt(0)
	s_barrier
	s_setprio 1
	s_waitcnt lgkmcnt(0)
	v_mfma_f32_16x16x32_bf16 v[60:63], v[138:141], v[174:177], v[60:63]
	v_mfma_f32_16x16x32_bf16 v[60:63], v[142:145], v[178:181], v[60:63]
	v_mfma_f32_16x16x32_bf16 v[56:59], v[146:149], v[174:177], v[56:59]
	v_mfma_f32_16x16x32_bf16 v[56:59], v[154:157], v[178:181], v[56:59]
	v_mfma_f32_16x16x32_bf16 v[28:31], v[158:161], v[174:177], v[28:31]
	v_mfma_f32_16x16x32_bf16 v[28:31], v[162:165], v[178:181], v[28:31]
	v_mfma_f32_16x16x32_bf16 v[24:27], v[166:169], v[174:177], v[24:27]
	v_mfma_f32_16x16x32_bf16 v[24:27], v[170:173], v[178:181], v[24:27]
	v_mfma_f32_16x16x32_bf16 v[16:19], v[166:169], v[182:185], v[16:19]
	v_mfma_f32_16x16x32_bf16 v[16:19], v[170:173], v[186:189], v[16:19]
	v_mfma_f32_16x16x32_bf16 v[20:23], v[158:161], v[182:185], v[20:23]
	v_mfma_f32_16x16x32_bf16 v[20:23], v[162:165], v[186:189], v[20:23]
	v_mfma_f32_16x16x32_bf16 v[48:51], v[146:149], v[182:185], v[48:51]
	v_mfma_f32_16x16x32_bf16 v[48:51], v[154:157], v[186:189], v[48:51]
	v_mfma_f32_16x16x32_bf16 v[52:55], v[138:141], v[182:185], v[52:55]
	v_mfma_f32_16x16x32_bf16 v[52:55], v[142:145], v[186:189], v[52:55]
	s_setprio 0
	s_setprio 1
	v_mfma_f32_16x16x32_bf16 v[44:47], v[138:141], v[190:193], v[44:47]
	v_mfma_f32_16x16x32_bf16 v[44:47], v[142:145], v[194:197], v[44:47]
	v_mfma_f32_16x16x32_bf16 v[40:43], v[146:149], v[190:193], v[40:43]
	v_mfma_f32_16x16x32_bf16 v[40:43], v[154:157], v[194:197], v[40:43]
	v_mfma_f32_16x16x32_bf16 v[12:15], v[158:161], v[190:193], v[12:15]
	v_mfma_f32_16x16x32_bf16 v[12:15], v[162:165], v[194:197], v[12:15]
	v_mfma_f32_16x16x32_bf16 v[8:11], v[166:169], v[190:193], v[8:11]
	v_mfma_f32_16x16x32_bf16 v[8:11], v[170:173], v[194:197], v[8:11]
	s_setprio 2
	s_barrier
	v_mfma_f32_16x16x32_bf16 v[0:3], v[166:169], v[198:201], v[0:3]
	v_mfma_f32_16x16x32_bf16 v[0:3], v[170:173], v[202:205], v[0:3]
	v_mfma_f32_16x16x32_bf16 v[4:7], v[158:161], v[198:201], v[4:7]
	v_mfma_f32_16x16x32_bf16 v[4:7], v[162:165], v[202:205], v[4:7]
	v_mfma_f32_16x16x32_bf16 v[32:35], v[146:149], v[198:201], v[32:35]
	v_mfma_f32_16x16x32_bf16 v[32:35], v[154:157], v[202:205], v[32:35]
	v_mfma_f32_16x16x32_bf16 v[36:39], v[138:141], v[198:201], v[36:39]
	v_mfma_f32_16x16x32_bf16 v[36:39], v[142:145], v[202:205], v[36:39]
	s_setprio 0
	s_add_i32 s47, 0, 0x18000
	s_add_i32 s64, 0, 0x1c000
	v_add_u32_e32 v154, s47, v150
	v_add_u32_e32 v170, s64, v150
	ds_read_b128 v[138:141], v154
	ds_read_b128 v[142:145], v154 offset:1024
	ds_read_b128 v[146:149], v154 offset:2048
	ds_read_b128 v[154:157], v154 offset:3072
	ds_read_b128 v[158:161], v170
	ds_read_b128 v[162:165], v170 offset:1024
	ds_read_b128 v[166:169], v170 offset:2048
	ds_read_b128 v[170:173], v170 offset:3072
	s_mov_b32 m0, s48
	ds_read_b128 v[174:177], v153 offset:32768
	ds_read_b128 v[178:181], v153 offset:33792
	ds_read_b128 v[182:185], v153 offset:34816
	ds_read_b128 v[186:189], v153 offset:35840
	ds_read_b128 v[190:193], v153 offset:36864
	ds_read_b128 v[194:197], v153 offset:37888
	ds_read_b128 v[198:201], v153 offset:38912
	ds_read_b128 v[202:205], v153 offset:39936
	s_add_u32 s98, s100, s6
	s_addc_u32 s99, s101, s7
	global_load_lds_dwordx4 v128, s[98:99]
	s_mov_b32 m0, s49
	s_nop 0
	s_add_u32 s98, s100, s8
	s_addc_u32 s99, s101, s9
	global_load_lds_dwordx4 v128, s[98:99]
	s_waitcnt vmcnt(8)
	s_waitcnt lgkmcnt(0)
	s_barrier
	s_setprio 1
	s_waitcnt lgkmcnt(0)
	v_mfma_f32_16x16x32_bf16 v[124:127], v[138:141], v[174:177], v[124:127]
	v_mfma_f32_16x16x32_bf16 v[124:127], v[142:145], v[178:181], v[124:127]
	v_mfma_f32_16x16x32_bf16 v[120:123], v[146:149], v[174:177], v[120:123]
	v_mfma_f32_16x16x32_bf16 v[120:123], v[154:157], v[178:181], v[120:123]
	v_mfma_f32_16x16x32_bf16 v[92:95], v[158:161], v[174:177], v[92:95]
	v_mfma_f32_16x16x32_bf16 v[92:95], v[162:165], v[178:181], v[92:95]
	v_mfma_f32_16x16x32_bf16 v[88:91], v[166:169], v[174:177], v[88:91]
	v_mfma_f32_16x16x32_bf16 v[88:91], v[170:173], v[178:181], v[88:91]
	v_mfma_f32_16x16x32_bf16 v[80:83], v[166:169], v[182:185], v[80:83]
	v_mfma_f32_16x16x32_bf16 v[80:83], v[170:173], v[186:189], v[80:83]
	v_mfma_f32_16x16x32_bf16 v[84:87], v[158:161], v[182:185], v[84:87]
	v_mfma_f32_16x16x32_bf16 v[84:87], v[162:165], v[186:189], v[84:87]
	v_mfma_f32_16x16x32_bf16 v[112:115], v[146:149], v[182:185], v[112:115]
	v_mfma_f32_16x16x32_bf16 v[112:115], v[154:157], v[186:189], v[112:115]
	v_mfma_f32_16x16x32_bf16 v[116:119], v[138:141], v[182:185], v[116:119]
	v_mfma_f32_16x16x32_bf16 v[116:119], v[142:145], v[186:189], v[116:119]
	s_setprio 0
	s_setprio 1
	v_mfma_f32_16x16x32_bf16 v[108:111], v[138:141], v[190:193], v[108:111]
	v_mfma_f32_16x16x32_bf16 v[108:111], v[142:145], v[194:197], v[108:111]
	v_mfma_f32_16x16x32_bf16 v[104:107], v[146:149], v[190:193], v[104:107]
	v_mfma_f32_16x16x32_bf16 v[104:107], v[154:157], v[194:197], v[104:107]
	v_mfma_f32_16x16x32_bf16 v[76:79], v[158:161], v[190:193], v[76:79]
	v_mfma_f32_16x16x32_bf16 v[76:79], v[162:165], v[194:197], v[76:79]
	v_mfma_f32_16x16x32_bf16 v[72:75], v[166:169], v[190:193], v[72:75]
	v_mfma_f32_16x16x32_bf16 v[72:75], v[170:173], v[194:197], v[72:75]
	s_setprio 2
	s_barrier
	v_mfma_f32_16x16x32_bf16 v[64:67], v[166:169], v[198:201], v[64:67]
	v_mfma_f32_16x16x32_bf16 v[64:67], v[170:173], v[202:205], v[64:67]
	v_mfma_f32_16x16x32_bf16 v[68:71], v[158:161], v[198:201], v[68:71]
	v_mfma_f32_16x16x32_bf16 v[68:71], v[162:165], v[202:205], v[68:71]
	v_mfma_f32_16x16x32_bf16 v[96:99], v[146:149], v[198:201], v[96:99]
	v_mfma_f32_16x16x32_bf16 v[96:99], v[154:157], v[202:205], v[96:99]
	v_mfma_f32_16x16x32_bf16 v[100:103], v[138:141], v[198:201], v[100:103]
	v_mfma_f32_16x16x32_bf16 v[100:103], v[142:145], v[202:205], v[100:103]
	s_setprio 0
	s_add_i32 s47, s47, s24
	s_mov_b32 m0, s47
	ds_read_b128 v[174:177], v153 offset:49152
	ds_read_b128 v[178:181], v153 offset:50176
	ds_read_b128 v[182:185], v153 offset:51200
	ds_read_b128 v[186:189], v153 offset:52224
	ds_read_b128 v[190:193], v153 offset:53248
	ds_read_b128 v[194:197], v153 offset:54272
	ds_read_b128 v[198:201], v153 offset:55296
	ds_read_b128 v[202:205], v153 offset:56320
	s_add_u32 s98, s66, s16
	s_addc_u32 s99, s67, s17
	global_load_lds_dwordx4 v130, s[98:99]
	s_add_i32 m0, s47, 0x2000
	s_add_i32 s47, s64, s24
	s_add_u32 s98, s66, s20
	s_addc_u32 s99, s67, s21
	global_load_lds_dwordx4 v130, s[98:99]
	s_mov_b32 m0, s47
	s_add_u32 s98, s66, s34
	s_addc_u32 s99, s67, s35
	global_load_lds_dwordx4 v130, s[98:99]
	s_add_i32 m0, s47, 0x2000
	s_nop 0
	s_add_u32 s98, s66, s36
	s_addc_u32 s99, s67, s37
	global_load_lds_dwordx4 v130, s[98:99]
	s_mov_b32 m0, s51
	s_nop 0
	s_add_u32 s98, s100, s16
	s_addc_u32 s99, s101, s17
	global_load_lds_dwordx4 v128, s[98:99]
	s_mov_b32 m0, s52
	s_nop 0
	s_add_u32 s98, s100, s20
	s_addc_u32 s99, s101, s21
	global_load_lds_dwordx4 v128, s[98:99]
	s_waitcnt vmcnt(8)
	s_waitcnt lgkmcnt(0)
	s_barrier
	s_setprio 1
	s_waitcnt lgkmcnt(0)
	v_mfma_f32_16x16x32_bf16 v[60:63], v[138:141], v[174:177], v[60:63]
	v_mfma_f32_16x16x32_bf16 v[60:63], v[142:145], v[178:181], v[60:63]
	v_mfma_f32_16x16x32_bf16 v[56:59], v[146:149], v[174:177], v[56:59]
	v_mfma_f32_16x16x32_bf16 v[56:59], v[154:157], v[178:181], v[56:59]
	v_mfma_f32_16x16x32_bf16 v[28:31], v[158:161], v[174:177], v[28:31]
	v_mfma_f32_16x16x32_bf16 v[28:31], v[162:165], v[178:181], v[28:31]
	v_mfma_f32_16x16x32_bf16 v[24:27], v[166:169], v[174:177], v[24:27]
	v_mfma_f32_16x16x32_bf16 v[24:27], v[170:173], v[178:181], v[24:27]
	v_mfma_f32_16x16x32_bf16 v[16:19], v[166:169], v[182:185], v[16:19]
	v_mfma_f32_16x16x32_bf16 v[16:19], v[170:173], v[186:189], v[16:19]
	v_mfma_f32_16x16x32_bf16 v[20:23], v[158:161], v[182:185], v[20:23]
	v_mfma_f32_16x16x32_bf16 v[20:23], v[162:165], v[186:189], v[20:23]
	v_mfma_f32_16x16x32_bf16 v[48:51], v[146:149], v[182:185], v[48:51]
	v_mfma_f32_16x16x32_bf16 v[48:51], v[154:157], v[186:189], v[48:51]
	v_mfma_f32_16x16x32_bf16 v[52:55], v[138:141], v[182:185], v[52:55]
	v_mfma_f32_16x16x32_bf16 v[52:55], v[142:145], v[186:189], v[52:55]
	s_setprio 0
	s_setprio 1
	v_mfma_f32_16x16x32_bf16 v[44:47], v[138:141], v[190:193], v[44:47]
	v_mfma_f32_16x16x32_bf16 v[44:47], v[142:145], v[194:197], v[44:47]
	v_mfma_f32_16x16x32_bf16 v[40:43], v[146:149], v[190:193], v[40:43]
	v_mfma_f32_16x16x32_bf16 v[40:43], v[154:157], v[194:197], v[40:43]
	v_mfma_f32_16x16x32_bf16 v[12:15], v[158:161], v[190:193], v[12:15]
	v_mfma_f32_16x16x32_bf16 v[12:15], v[162:165], v[194:197], v[12:15]
	v_mfma_f32_16x16x32_bf16 v[8:11], v[166:169], v[190:193], v[8:11]
	v_mfma_f32_16x16x32_bf16 v[8:11], v[170:173], v[194:197], v[8:11]
	s_setprio 2
	s_barrier
	v_mfma_f32_16x16x32_bf16 v[0:3], v[166:169], v[198:201], v[0:3]
	v_mfma_f32_16x16x32_bf16 v[0:3], v[170:173], v[202:205], v[0:3]
	v_mfma_f32_16x16x32_bf16 v[4:7], v[158:161], v[198:201], v[4:7]
	v_mfma_f32_16x16x32_bf16 v[4:7], v[162:165], v[202:205], v[4:7]
	v_mfma_f32_16x16x32_bf16 v[32:35], v[146:149], v[198:201], v[32:35]
	v_mfma_f32_16x16x32_bf16 v[32:35], v[154:157], v[202:205], v[32:35]
	v_mfma_f32_16x16x32_bf16 v[36:39], v[138:141], v[198:201], v[36:39]
	v_mfma_f32_16x16x32_bf16 v[36:39], v[142:145], v[202:205], v[36:39]
	s_setprio 0
	s_add_i32 s46, s46, 2
	s_add_u32 s62, s62, 0x100
	s_addc_u32 s63, s63, 0
	s_add_u32 s44, s44, 0x100
	s_addc_u32 s45, s45, 0
	s_cmpk_gt_u32 s46, 0xa9
	s_cbranch_scc0 .LBB0_1034
	s_and_b64 vcc, exec, s[38:39]
	s_cbranch_vccz .LBB0_1037
	s_barrier

.LBB0_1180:
	ds_read_b128 v[112:115], v181
	ds_read_b128 v[116:119], v181 offset:1024
	ds_read_b128 v[128:131], v181 offset:2048
	ds_read_b128 v[142:145], v181 offset:3072
	ds_read_b128 v[146:149], v202
	ds_read_b128 v[150:153], v202 offset:1024
	ds_read_b128 v[154:157], v202 offset:2048
	ds_read_b128 v[168:171], v202 offset:3072
	s_add_u32 s49, s46, 0xfff80080
	s_addc_u32 s70, s47, -1
	s_cmp_eq_u32 s48, 28
	s_cselect_b32 s71, s39, s70
	s_cselect_b32 s70, s66, s49
	s_cselect_b32 s73, s37, s69
	s_cselect_b32 s72, s67, s68
	s_add_i32 m0, s45, 0xc000
	ds_read_b128 v[172:175], v203
	ds_read_b128 v[182:185], v203 offset:1024
	ds_read_b128 v[186:189], v203 offset:2048
	ds_read_b128 v[190:193], v203 offset:3072
	ds_read_b128 v[194:197], v203 offset:4096
	ds_read_b128 v[198:201], v203 offset:5120
	ds_read_b128 v[206:209], v203 offset:6144
	ds_read_b128 v[210:213], v203 offset:7168
	global_load_lds_dwordx4 v162, s[46:47]
	s_add_i32 m0, s45, 0xe000
	s_nop 0
	s_add_u32 s98, s46, s2
	s_addc_u32 s99, s47, s3
	global_load_lds_dwordx4 v162, s[98:99]
	s_waitcnt vmcnt(8)
	s_waitcnt lgkmcnt(0)
	s_barrier
	s_setprio 1
	s_waitcnt lgkmcnt(0)
	v_mfma_i32_16x16x64_i8 v[138:141], v[112:115], v[172:175], v[138:141]
	v_mfma_i32_16x16x64_i8 v[132:135], v[128:131], v[172:175], v[134:137]
	v_mfma_i32_16x16x64_i8 v[124:127], v[112:115], v[186:189], v[124:127]
	v_mfma_i32_16x16x64_i8 v[120:123], v[128:131], v[186:189], v[120:123]
	v_mfma_i32_16x16x64_i8 v[108:111], v[112:115], v[194:197], v[108:111]
	v_mfma_i32_16x16x64_i8 v[104:107], v[128:131], v[194:197], v[104:107]
	v_mfma_i32_16x16x64_i8 v[100:103], v[112:115], v[206:209], v[100:103]
	v_mfma_i32_16x16x64_i8 v[96:99], v[128:131], v[206:209], v[96:99]
	v_mfma_i32_16x16x64_i8 v[138:141], v[116:119], v[182:185], v[138:141]
	v_mfma_i32_16x16x64_i8 v[132:135], v[142:145], v[182:185], v[132:135]
	v_mfma_i32_16x16x64_i8 v[124:127], v[116:119], v[190:193], v[124:127]
	v_mfma_i32_16x16x64_i8 v[120:123], v[142:145], v[190:193], v[120:123]
	v_mfma_i32_16x16x64_i8 v[108:111], v[116:119], v[198:201], v[108:111]
	v_mfma_i32_16x16x64_i8 v[104:107], v[142:145], v[198:201], v[104:107]
	v_mfma_i32_16x16x64_i8 v[100:103], v[116:119], v[210:213], v[100:103]
	v_mfma_i32_16x16x64_i8 v[96:99], v[142:145], v[210:213], v[96:99]
	s_setprio 0
	s_setprio 1
	v_mfma_i32_16x16x64_i8 v[60:63], v[146:149], v[172:175], v[60:63]
	v_mfma_i32_16x16x64_i8 v[60:63], v[150:153], v[182:185], v[60:63]
	v_mfma_i32_16x16x64_i8 v[56:59], v[154:157], v[172:175], v[56:59]
	v_mfma_i32_16x16x64_i8 v[56:59], v[168:171], v[182:185], v[56:59]
	v_mfma_i32_16x16x64_i8 v[52:55], v[146:149], v[186:189], v[52:55]
	v_mfma_i32_16x16x64_i8 v[52:55], v[150:153], v[190:193], v[52:55]
	v_mfma_i32_16x16x64_i8 v[48:51], v[154:157], v[186:189], v[48:51]
	v_mfma_i32_16x16x64_i8 v[48:51], v[168:171], v[190:193], v[48:51]
	s_setprio 2
	s_barrier
	v_mfma_i32_16x16x64_i8 v[44:47], v[146:149], v[194:197], v[44:47]
	v_mfma_i32_16x16x64_i8 v[44:47], v[150:153], v[198:201], v[44:47]
	v_mfma_i32_16x16x64_i8 v[40:43], v[154:157], v[194:197], v[40:43]
	v_mfma_i32_16x16x64_i8 v[40:43], v[168:171], v[198:201], v[40:43]
	v_mfma_i32_16x16x64_i8 v[36:39], v[146:149], v[206:209], v[36:39]
	v_mfma_i32_16x16x64_i8 v[36:39], v[150:153], v[210:213], v[36:39]
	v_mfma_i32_16x16x64_i8 v[32:35], v[154:157], v[206:209], v[32:35]
	v_mfma_i32_16x16x64_i8 v[32:35], v[168:171], v[210:213], v[32:35]
	s_setprio 0
	s_add_i32 s49, s61, s33
	s_mov_b32 m0, s49
	ds_read_b128 v[172:175], v203 offset:16384
	ds_read_b128 v[182:185], v203 offset:17408
	ds_read_b128 v[186:189], v203 offset:18432
	ds_read_b128 v[190:193], v203 offset:19456
	ds_read_b128 v[194:197], v203 offset:20480
	ds_read_b128 v[198:201], v203 offset:21504
	ds_read_b128 v[206:209], v203 offset:22528
	ds_read_b128 v[210:213], v203 offset:23552
	global_load_lds_dwordx4 v160, s[72:73]
	s_add_i32 m0, s49, 0x2000
	s_add_i32 s49, s62, s33
	s_add_u32 s98, s72, s2
	s_addc_u32 s99, s73, s3
	global_load_lds_dwordx4 v160, s[98:99]
	s_mov_b32 m0, s49
	s_mov_b64 s[100:101], s[70:71]
	s_add_u32 s98, s72, s6
	s_addc_u32 s99, s73, s7
	global_load_lds_dwordx4 v160, s[98:99]
	s_add_i32 m0, s49, 0x2000
	s_nop 0
	s_add_u32 s98, s72, s8
	s_addc_u32 s99, s73, s9
	global_load_lds_dwordx4 v160, s[98:99]
	s_mov_b32 m0, s45
	s_nop 0
	global_load_lds_dwordx4 v158, s[70:71]
	s_mov_b32 m0, s50
	s_nop 0
	s_add_u32 s98, s70, s2
	s_addc_u32 s99, s71, s3
	global_load_lds_dwordx4 v158, s[98:99]
	s_waitcnt vmcnt(8)
	s_waitcnt lgkmcnt(0)
	s_barrier
	s_setprio 1
	s_waitcnt lgkmcnt(0)
	v_mfma_i32_16x16x64_i8 v[92:95], v[112:115], v[172:175], v[92:95]
	v_mfma_i32_16x16x64_i8 v[92:95], v[116:119], v[182:185], v[92:95]
	v_mfma_i32_16x16x64_i8 v[88:91], v[128:131], v[172:175], v[88:91]
	v_mfma_i32_16x16x64_i8 v[88:91], v[142:145], v[182:185], v[88:91]
	v_mfma_i32_16x16x64_i8 v[28:31], v[146:149], v[172:175], v[28:31]
	v_mfma_i32_16x16x64_i8 v[28:31], v[150:153], v[182:185], v[28:31]
	v_mfma_i32_16x16x64_i8 v[24:27], v[154:157], v[172:175], v[24:27]
	v_mfma_i32_16x16x64_i8 v[24:27], v[168:171], v[182:185], v[24:27]
	v_mfma_i32_16x16x64_i8 v[16:19], v[154:157], v[186:189], v[16:19]
	v_mfma_i32_16x16x64_i8 v[16:19], v[168:171], v[190:193], v[16:19]
	v_mfma_i32_16x16x64_i8 v[20:23], v[146:149], v[186:189], v[20:23]
	v_mfma_i32_16x16x64_i8 v[20:23], v[150:153], v[190:193], v[20:23]
	v_mfma_i32_16x16x64_i8 v[80:83], v[128:131], v[186:189], v[80:83]
	v_mfma_i32_16x16x64_i8 v[80:83], v[142:145], v[190:193], v[80:83]
	v_mfma_i32_16x16x64_i8 v[84:87], v[112:115], v[186:189], v[84:87]
	v_mfma_i32_16x16x64_i8 v[84:87], v[116:119], v[190:193], v[84:87]
	s_setprio 0
	s_setprio 1
	v_mfma_i32_16x16x64_i8 v[76:79], v[112:115], v[194:197], v[76:79]
	v_mfma_i32_16x16x64_i8 v[76:79], v[116:119], v[198:201], v[76:79]
	v_mfma_i32_16x16x64_i8 v[72:75], v[128:131], v[194:197], v[72:75]
	v_mfma_i32_16x16x64_i8 v[72:75], v[142:145], v[198:201], v[72:75]
	v_mfma_i32_16x16x64_i8 v[12:15], v[146:149], v[194:197], v[12:15]
	v_mfma_i32_16x16x64_i8 v[12:15], v[150:153], v[198:201], v[12:15]
	v_mfma_i32_16x16x64_i8 v[8:11], v[154:157], v[194:197], v[8:11]
	v_mfma_i32_16x16x64_i8 v[8:11], v[168:171], v[198:201], v[8:11]
	s_setprio 2
	s_barrier
	v_mfma_i32_16x16x64_i8 v[0:3], v[154:157], v[206:209], v[0:3]
	v_mfma_i32_16x16x64_i8 v[0:3], v[168:171], v[210:213], v[0:3]
	v_mfma_i32_16x16x64_i8 v[4:7], v[146:149], v[206:209], v[4:7]
	v_mfma_i32_16x16x64_i8 v[4:7], v[150:153], v[210:213], v[4:7]
	v_mfma_i32_16x16x64_i8 v[64:67], v[128:131], v[206:209], v[64:67]
	v_mfma_i32_16x16x64_i8 v[64:67], v[142:145], v[210:213], v[64:67]
	v_mfma_i32_16x16x64_i8 v[68:71], v[112:115], v[206:209], v[68:71]
	v_mfma_i32_16x16x64_i8 v[68:71], v[116:119], v[210:213], v[68:71]
	s_setprio 0
	s_add_i32 s49, 0, 0x18000
	v_add_u32_e32 v136, s49, v179
	s_add_i32 s70, 0, 0x1c000
	ds_read_b128 v[112:115], v136
	ds_read_b128 v[116:119], v136 offset:1024
	ds_read_b128 v[128:131], v136 offset:2048
	ds_read_b128 v[142:145], v136 offset:3072
	v_add_u32_e32 v136, s70, v179
	ds_read_b128 v[146:149], v136
	ds_read_b128 v[150:153], v136 offset:1024
	ds_read_b128 v[154:157], v136 offset:2048
	ds_read_b128 v[168:171], v136 offset:3072
	s_mov_b32 m0, s51
	ds_read_b128 v[172:175], v203 offset:32768
	ds_read_b128 v[182:185], v203 offset:33792
	ds_read_b128 v[186:189], v203 offset:34816
	ds_read_b128 v[190:193], v203 offset:35840
	ds_read_b128 v[194:197], v203 offset:36864
	ds_read_b128 v[198:201], v203 offset:37888
	ds_read_b128 v[206:209], v203 offset:38912
	ds_read_b128 v[210:213], v203 offset:39936
	s_add_u32 s98, s100, s6
	s_addc_u32 s99, s101, s7
	global_load_lds_dwordx4 v158, s[98:99]
	s_mov_b32 m0, s52
	s_nop 0
	s_add_u32 s98, s100, s8
	s_addc_u32 s99, s101, s9
	global_load_lds_dwordx4 v158, s[98:99]
	s_waitcnt vmcnt(8)
	s_waitcnt lgkmcnt(0)
	s_barrier
	s_setprio 1
	s_waitcnt lgkmcnt(0)
	v_mfma_i32_16x16x64_i8 v[136:139], v[112:115], v[172:175], v[138:141]
	v_mfma_i32_16x16x64_i8 v[132:135], v[128:131], v[172:175], v[132:135]
	v_mfma_i32_16x16x64_i8 v[124:127], v[112:115], v[186:189], v[124:127]
	v_mfma_i32_16x16x64_i8 v[120:123], v[128:131], v[186:189], v[120:123]
	v_mfma_i32_16x16x64_i8 v[108:111], v[112:115], v[194:197], v[108:111]
	v_mfma_i32_16x16x64_i8 v[104:107], v[128:131], v[194:197], v[104:107]
	v_mfma_i32_16x16x64_i8 v[100:103], v[112:115], v[206:209], v[100:103]
	v_mfma_i32_16x16x64_i8 v[96:99], v[128:131], v[206:209], v[96:99]
	v_mfma_i32_16x16x64_i8 v[138:141], v[116:119], v[182:185], v[136:139]
	v_mfma_i32_16x16x64_i8 v[134:137], v[142:145], v[182:185], v[132:135]
	v_mfma_i32_16x16x64_i8 v[124:127], v[116:119], v[190:193], v[124:127]
	v_mfma_i32_16x16x64_i8 v[120:123], v[142:145], v[190:193], v[120:123]
	v_mfma_i32_16x16x64_i8 v[108:111], v[116:119], v[198:201], v[108:111]
	v_mfma_i32_16x16x64_i8 v[104:107], v[142:145], v[198:201], v[104:107]
	v_mfma_i32_16x16x64_i8 v[100:103], v[116:119], v[210:213], v[100:103]
	v_mfma_i32_16x16x64_i8 v[96:99], v[142:145], v[210:213], v[96:99]
	s_setprio 0
	s_setprio 1
	v_mfma_i32_16x16x64_i8 v[60:63], v[146:149], v[172:175], v[60:63]
	v_mfma_i32_16x16x64_i8 v[60:63], v[150:153], v[182:185], v[60:63]
	v_mfma_i32_16x16x64_i8 v[56:59], v[154:157], v[172:175], v[56:59]
	v_mfma_i32_16x16x64_i8 v[56:59], v[168:171], v[182:185], v[56:59]
	v_mfma_i32_16x16x64_i8 v[52:55], v[146:149], v[186:189], v[52:55]
	v_mfma_i32_16x16x64_i8 v[52:55], v[150:153], v[190:193], v[52:55]
	v_mfma_i32_16x16x64_i8 v[48:51], v[154:157], v[186:189], v[48:51]
	v_mfma_i32_16x16x64_i8 v[48:51], v[168:171], v[190:193], v[48:51]
	s_setprio 2
	s_barrier
	v_mfma_i32_16x16x64_i8 v[44:47], v[146:149], v[194:197], v[44:47]
	v_mfma_i32_16x16x64_i8 v[44:47], v[150:153], v[198:201], v[44:47]
	v_mfma_i32_16x16x64_i8 v[40:43], v[154:157], v[194:197], v[40:43]
	v_mfma_i32_16x16x64_i8 v[40:43], v[168:171], v[198:201], v[40:43]
	v_mfma_i32_16x16x64_i8 v[36:39], v[146:149], v[206:209], v[36:39]
	v_mfma_i32_16x16x64_i8 v[36:39], v[150:153], v[210:213], v[36:39]
	v_mfma_i32_16x16x64_i8 v[32:35], v[154:157], v[206:209], v[32:35]
	v_mfma_i32_16x16x64_i8 v[32:35], v[168:171], v[210:213], v[32:35]
	s_setprio 0
	s_add_i32 s49, s49, s33
	s_mov_b32 m0, s49
	ds_read_b128 v[172:175], v203 offset:49152
	ds_read_b128 v[182:185], v203 offset:50176
	ds_read_b128 v[186:189], v203 offset:51200
	ds_read_b128 v[190:193], v203 offset:52224
	ds_read_b128 v[194:197], v203 offset:53248
	ds_read_b128 v[198:201], v203 offset:54272
	ds_read_b128 v[206:209], v203 offset:55296
	ds_read_b128 v[210:213], v203 offset:56320
	s_add_u32 s98, s72, s16
	s_addc_u32 s99, s73, s17
	global_load_lds_dwordx4 v160, s[98:99]
	s_add_i32 m0, s49, 0x2000
	s_add_i32 s49, s70, s33
	s_add_u32 s98, s72, s18
	s_addc_u32 s99, s73, s19
	global_load_lds_dwordx4 v160, s[98:99]
	s_mov_b32 m0, s49
	s_nop 0
	s_add_u32 s98, s72, s20
	s_addc_u32 s99, s73, s21
	global_load_lds_dwordx4 v160, s[98:99]
	s_add_i32 m0, s49, 0x2000
	s_nop 0
	s_add_u32 s98, s72, s30
	s_addc_u32 s99, s73, s31
	global_load_lds_dwordx4 v160, s[98:99]
	s_mov_b32 m0, s54
	s_nop 0
	s_add_u32 s98, s100, s16
	s_addc_u32 s99, s101, s17
	global_load_lds_dwordx4 v158, s[98:99]
	s_mov_b32 m0, s55
	s_nop 0
	s_add_u32 s98, s100, s18
	s_addc_u32 s99, s101, s19
	global_load_lds_dwordx4 v158, s[98:99]
	s_waitcnt vmcnt(8)
	s_waitcnt lgkmcnt(0)
	s_barrier
	s_setprio 1
	s_waitcnt lgkmcnt(0)
	v_mfma_i32_16x16x64_i8 v[92:95], v[112:115], v[172:175], v[92:95]
	v_mfma_i32_16x16x64_i8 v[92:95], v[116:119], v[182:185], v[92:95]
	v_mfma_i32_16x16x64_i8 v[88:91], v[128:131], v[172:175], v[88:91]
	v_mfma_i32_16x16x64_i8 v[88:91], v[142:145], v[182:185], v[88:91]
	v_mfma_i32_16x16x64_i8 v[28:31], v[146:149], v[172:175], v[28:31]
	v_mfma_i32_16x16x64_i8 v[28:31], v[150:153], v[182:185], v[28:31]
	v_mfma_i32_16x16x64_i8 v[24:27], v[154:157], v[172:175], v[24:27]
	v_mfma_i32_16x16x64_i8 v[24:27], v[168:171], v[182:185], v[24:27]
	v_mfma_i32_16x16x64_i8 v[16:19], v[154:157], v[186:189], v[16:19]
	v_mfma_i32_16x16x64_i8 v[16:19], v[168:171], v[190:193], v[16:19]
	v_mfma_i32_16x16x64_i8 v[20:23], v[146:149], v[186:189], v[20:23]
	v_mfma_i32_16x16x64_i8 v[20:23], v[150:153], v[190:193], v[20:23]
	v_mfma_i32_16x16x64_i8 v[80:83], v[128:131], v[186:189], v[80:83]
	v_mfma_i32_16x16x64_i8 v[80:83], v[142:145], v[190:193], v[80:83]
	v_mfma_i32_16x16x64_i8 v[84:87], v[112:115], v[186:189], v[84:87]
	v_mfma_i32_16x16x64_i8 v[84:87], v[116:119], v[190:193], v[84:87]
	s_setprio 0
	s_setprio 1
	v_mfma_i32_16x16x64_i8 v[76:79], v[112:115], v[194:197], v[76:79]
	v_mfma_i32_16x16x64_i8 v[76:79], v[116:119], v[198:201], v[76:79]
	v_mfma_i32_16x16x64_i8 v[72:75], v[128:131], v[194:197], v[72:75]
	v_mfma_i32_16x16x64_i8 v[72:75], v[142:145], v[198:201], v[72:75]
	v_mfma_i32_16x16x64_i8 v[12:15], v[146:149], v[194:197], v[12:15]
	v_mfma_i32_16x16x64_i8 v[12:15], v[150:153], v[198:201], v[12:15]
	v_mfma_i32_16x16x64_i8 v[8:11], v[154:157], v[194:197], v[8:11]
	v_mfma_i32_16x16x64_i8 v[8:11], v[168:171], v[198:201], v[8:11]
	s_setprio 2
	s_barrier
	v_mfma_i32_16x16x64_i8 v[0:3], v[154:157], v[206:209], v[0:3]
	v_mfma_i32_16x16x64_i8 v[0:3], v[168:171], v[210:213], v[0:3]
	v_mfma_i32_16x16x64_i8 v[4:7], v[146:149], v[206:209], v[4:7]
	v_mfma_i32_16x16x64_i8 v[4:7], v[150:153], v[210:213], v[4:7]
	v_mfma_i32_16x16x64_i8 v[64:67], v[128:131], v[206:209], v[64:67]
	v_mfma_i32_16x16x64_i8 v[64:67], v[142:145], v[210:213], v[64:67]
	v_mfma_i32_16x16x64_i8 v[68:71], v[112:115], v[206:209], v[68:71]
	v_mfma_i32_16x16x64_i8 v[68:71], v[116:119], v[210:213], v[68:71]
	s_setprio 0
	s_add_i32 s48, s48, 2
	s_add_u32 s68, s68, 0x100
	s_addc_u32 s69, s69, 0
	s_add_u32 s46, s46, 0x100
	s_addc_u32 s47, s47, 0
	s_cmp_gt_u32 s48, 29
	s_cbranch_scc0 .LBB0_1180
	s_and_b64 vcc, exec, s[34:35]
	s_cbranch_vccz .LBB0_1183
	s_barrier
